# batched residual-epilogue base loads in P12 and P8
# baseline (speedup 1.0000x reference)
.LBB0_693:
	s_cmp_lt_u32 s2, 8
	s_barrier
	s_cbranch_scc1 .LBB0_950
	s_mov_b64 exec, -1
	v_readlane_b32 s0, v254, 0
	v_readlane_b32 s1, v254, 1
	s_nop 4
	s_load_dwordx2 s[56:57], s[0:1], 0xa8
	s_load_dwordx2 s[58:59], s[0:1], 0xc0
	s_load_dwordx2 s[60:61], s[0:1], 0x88
	s_load_dwordx2 s[62:63], s[0:1], 0x78
	s_load_dwordx2 s[64:65], s[0:1], 0x80
	s_load_dwordx2 s[66:67], s[0:1], 0x90
	s_load_dwordx2 s[68:69], s[0:1], 0xa0
	s_load_dwordx2 s[70:71], s[0:1], 0x48
	s_load_dwordx2 s[72:73], s[0:1], 0xd8
	s_load_dword s3, s[0:1], 0xe8
	v_readfirstlane_b32 s4, v0
	v_and_b32_e32 v7, 63, v0
	s_lshr_b32 s4, s4, 6
	v_lshrrev_b32_e32 v1, 3, v7
	v_and_b32_e32 v2, 7, v7
	s_lshl_b32 s5, s4, 14
	v_lshlrev_b32_e32 v5, 5, v2
	s_movk_i32 s14, 0x420
	v_mul_u32_u24_e32 v4, s14, v2
	v_lshlrev_b32_e32 v2, 4, v2
	s_movk_i32 s14, 0x84
	v_mad_u32_u24 v3, v1, s14, v2
	v_lshl_add_u32 v4, v1, 2, v4
	v_add_u32_e32 v3, s5, v3
	v_add_u32_e32 v4, s5, v4
	v_mov_b32_e32 v207, v3
	v_add_u32_e32 v208, 1056, v3
	v_add_u32_e32 v209, 2112, v3
	v_add_u32_e32 v210, 3168, v3
	v_add_u32_e32 v211, 4224, v3
	v_add_u32_e32 v212, 5280, v3
	v_add_u32_e32 v213, 6336, v3
	v_add_u32_e32 v214, 7392, v3
	s_waitcnt lgkmcnt(0)
	s_sub_u32 s5, s2, 8
	s_lshl_b32 s5, s5, 3
	s_add_u32 s20, s5, s4
	s_sub_u32 s21, s3, 8
	s_lshl_b32 s21, s21, 3
	s_cmp_ge_u32 s20, 0x5600
	s_cbranch_scc1 .Lrc_p3call
	s_mov_b32 s42, 0
	s_mov_b32 s43, 0
	s_mov_b32 s26, s20
	s_cmp_lt_u32 s26, 0x2c00
	s_cbranch_scc1 .Ltrp3_i1_s0
	s_sub_u32 s26, s26, 0x2c00
	s_cmp_lt_u32 s26, 0x1600
	s_cbranch_scc1 .Ltrp3_i1_s1
	s_sub_u32 s26, s26, 0x1600
	s_cmp_lt_u32 s26, 0x800
	s_cbranch_scc1 .Ltrp3_i1_s2
	s_sub_u32 s26, s26, 0x800
	s_cmp_lt_u32 s26, 0x400
	s_cbranch_scc1 .Ltrp3_i1_s3
	s_sub_u32 s26, s26, 0x400
	s_cmp_lt_u32 s26, 0x400
	s_cbranch_scc1 .Ltrp3_i1_s4
	s_sub_u32 s26, s26, 0x400
	s_cmp_lt_u32 s26, 0x200
	s_cbranch_scc1 .Ltrp3_i1_s5
	s_sub_u32 s26, s26, 0x200
	s_branch .Ltrp3_i1_s6

.LBB0_2146:
	s_nop 15
	s_nop 15
	s_cmp_lt_i32 s56, 32
	s_mov_b64 s[58:59], -1
	s_cbranch_scc0 .LBB0_2165
	s_ashr_i32 s57, s56, 31
	s_lshl_b64 s[56:57], s[56:57], 8
	v_lshl_or_b32 v164, s12, 8, v166
	v_lshl_add_u64 v[160:161], s[56:57], 0, v[136:137]
	v_ashrrev_i32_e32 v165, 31, v164
	v_lshlrev_b64 v[162:163], 11, v[160:161]
	v_readlane_b32 s80, v254, 48
	v_lshl_add_u64 v[162:163], v[162:163], 0, v[164:165]
	v_readlane_b32 s81, v254, 49
	v_lshlrev_b64 v[176:177], 1, v[162:163]
	v_lshl_add_u64 v[178:179], s[20:21], 0, v[176:177]
	v_lshl_add_u64 v[174:175], v[162:163], 2, s[80:81]
	v_lshlrev_b32_e32 v252, 2, v162
	s_nop 4
	global_load_dwordx4 v[208:211], v252, s[80:81]
	global_load_dwordx4 v[212:215], v252, s[80:81] offset:64
	global_load_dwordx4 v[216:219], v252, s[80:81] offset:512
	global_load_dwordx4 v[220:223], v252, s[80:81] offset:576
	v_add_u32_e32 v200, 0x20000, v252
	global_load_dwordx4 v[224:227], v200, s[80:81]
	global_load_dwordx4 v[228:231], v200, s[80:81] offset:64
	global_load_dwordx4 v[192:195], v200, s[80:81] offset:512
	global_load_dwordx4 v[196:199], v200, s[80:81] offset:576
	s_waitcnt vmcnt(0)
	v_mov_b64_e32 v[170:171], v[208:209]
	v_mov_b64_e32 v[172:173], v[210:211]
	v_readlane_b32 s82, v254, 50
	v_readlane_b32 s83, v254, 51
	v_readlane_b32 s84, v254, 52
	v_readlane_b32 s85, v254, 53
	v_readlane_b32 s86, v254, 54
	v_readlane_b32 s87, v254, 55
	v_readlane_b32 s88, v254, 56
	v_readlane_b32 s89, v254, 57
	v_readlane_b32 s90, v254, 58
	v_readlane_b32 s91, v254, 59
	v_readlane_b32 s92, v254, 60
	v_readlane_b32 s93, v254, 61
	v_readlane_b32 s94, v254, 62
	v_readlane_b32 s95, v254, 63
	s_nop 0
	v_pk_add_f32 v[180:181], v[68:69], v[172:173]
	v_pk_add_f32 v[182:183], v[66:67], v[170:171]
	s_nop 0
	v_cvt_pk_bf16_f32 v170, v182, v183
	v_cvt_pk_bf16_f32 v171, v180, v181
	global_store_dwordx2 v[178:179], v[170:171], off
	v_mov_b64_e32 v[170:171], v[212:213]
	v_mov_b64_e32 v[172:173], v[214:215]
	v_or_b32_e32 v178, 32, v176
	v_mov_b32_e32 v179, v177
	v_lshl_add_u64 v[178:179], s[20:21], 0, v[178:179]
	s_nop 0
	v_pk_add_f32 v[184:185], v[64:65], v[172:173]
	v_pk_add_f32 v[186:187], v[62:63], v[170:171]
	s_nop 0
	v_cvt_pk_bf16_f32 v170, v186, v187
	v_cvt_pk_bf16_f32 v171, v184, v185
	global_store_dwordx2 v[178:179], v[170:171], off
	v_mov_b64_e32 v[170:171], v[216:217]
	v_mov_b64_e32 v[172:173], v[218:219]
	v_or_b32_e32 v178, 0x100, v176
	v_mov_b32_e32 v179, v177
	v_lshl_add_u64 v[178:179], s[20:21], 0, v[178:179]
	v_or_b32_e32 v176, 0x120, v176
	s_nop 0
	v_pk_add_f32 v[188:189], v[48:49], v[172:173]
	v_pk_add_f32 v[190:191], v[46:47], v[170:171]
	s_nop 0
	v_cvt_pk_bf16_f32 v170, v190, v191
	v_cvt_pk_bf16_f32 v171, v188, v189
	global_store_dwordx2 v[178:179], v[170:171], off
	v_mov_b64_e32 v[170:171], v[220:221]
	v_mov_b64_e32 v[172:173], v[222:223]
	v_lshl_add_u64 v[174:175], s[20:21], 0, v[176:177]
	v_mul_f32_e32 v176, v183, v183
	v_mul_f32_e32 v177, v181, v181
	v_fmac_f32_e32 v176, v182, v182
	v_fmac_f32_e32 v177, v180, v180
	v_add_f32_e32 v176, v176, v177
	v_mul_f32_e32 v177, v187, v187
	v_mul_f32_e32 v178, v185, v185
	v_fmac_f32_e32 v177, v186, v186
	v_fmac_f32_e32 v178, v184, v184
	v_add_f32_e32 v177, v177, v178
	v_add_f32_e32 v176, v176, v177
	v_mul_f32_e32 v177, v191, v191
	v_mul_f32_e32 v178, v189, v189
	v_fmac_f32_e32 v177, v190, v190
	v_fmac_f32_e32 v178, v188, v188
	v_add_f32_e32 v177, v177, v178
	v_add_f32_e32 v178, v176, v177
	s_nop 0
	v_pk_add_f32 v[172:173], v[40:41], v[172:173]
	v_pk_add_f32 v[170:171], v[38:39], v[170:171]
	s_nop 0
	v_cvt_pk_bf16_f32 v176, v170, v171
	v_cvt_pk_bf16_f32 v177, v172, v173
	v_mul_f32_e32 v171, v171, v171
	v_mul_f32_e32 v173, v173, v173
	v_fmac_f32_e32 v171, v170, v170
	v_fmac_f32_e32 v173, v172, v172
	v_add_f32_e32 v170, v171, v173
	v_add_f32_e32 v170, v178, v170
	v_mov_b32_e32 v171, v170
	s_nop 1
	v_permlane16_swap_b32_e32 v170, v171
	v_add_f32_e32 v170, v170, v171
	v_mov_b32_e32 v171, v170
	s_nop 1
	v_permlane32_swap_b32_e32 v170, v171
	global_store_dwordx2 v[174:175], v[176:177], off
	s_and_saveexec_b64 s[58:59], s[4:5]
	s_cbranch_execz .LBB0_2149
	s_lshl_b32 s0, s12, 2
	s_or_b32 s0, s0, s74
	s_ashr_i32 s1, s0, 31
	s_lshl_b64 s[0:1], s[0:1], 15
	s_add_u32 s0, s72, s0
	s_addc_u32 s1, s73, s1
	v_add_f32_e32 v172, v170, v171
	v_lshl_add_u64 v[170:171], v[160:161], 2, s[0:1]
	global_store_dword v[170:171], v172, off
.LBB0_2149:
	s_or_b64 exec, exec, s[58:59]
	v_lshl_add_u64 v[170:171], s[56:57], 0, v[138:139]
	v_lshlrev_b64 v[170:171], 11, v[170:171]
	v_readlane_b32 s80, v254, 48
	v_lshl_add_u64 v[174:175], v[170:171], 0, v[164:165]
	v_readlane_b32 s81, v254, 49
	v_readlane_b32 s82, v254, 50
	v_readlane_b32 s83, v254, 51
	v_lshl_add_u64 v[176:177], v[174:175], 2, s[80:81]
	v_mov_b64_e32 v[170:171], v[224:225]
	v_mov_b64_e32 v[172:173], v[226:227]
	v_lshlrev_b64 v[174:175], 1, v[174:175]
	v_lshl_add_u64 v[178:179], s[20:21], 0, v[174:175]
	v_readlane_b32 s84, v254, 52
	v_readlane_b32 s85, v254, 53
	v_readlane_b32 s86, v254, 54
	v_readlane_b32 s87, v254, 55
	v_readlane_b32 s88, v254, 56
	v_readlane_b32 s89, v254, 57
	v_readlane_b32 s90, v254, 58
	v_readlane_b32 s91, v254, 59
	v_readlane_b32 s92, v254, 60
	v_readlane_b32 s93, v254, 61
	v_readlane_b32 s94, v254, 62
	v_readlane_b32 s95, v254, 63
	s_nop 0
	v_pk_add_f32 v[180:181], v[60:61], v[172:173]
	v_pk_add_f32 v[182:183], v[58:59], v[170:171]
	s_nop 0
	v_cvt_pk_bf16_f32 v170, v182, v183
	v_cvt_pk_bf16_f32 v171, v180, v181
	global_store_dwordx2 v[178:179], v[170:171], off
	v_mov_b64_e32 v[170:171], v[228:229]
	v_mov_b64_e32 v[172:173], v[230:231]
	v_or_b32_e32 v178, 32, v174
	v_mov_b32_e32 v179, v175
	v_lshl_add_u64 v[178:179], s[20:21], 0, v[178:179]
	s_nop 0
	v_pk_add_f32 v[184:185], v[56:57], v[172:173]
	v_pk_add_f32 v[186:187], v[54:55], v[170:171]
	s_nop 0
	v_cvt_pk_bf16_f32 v170, v186, v187
	v_cvt_pk_bf16_f32 v171, v184, v185
	global_store_dwordx2 v[178:179], v[170:171], off
	v_mov_b64_e32 v[170:171], v[192:193]
	v_mov_b64_e32 v[172:173], v[194:195]
	v_or_b32_e32 v178, 0x100, v174
	v_mov_b32_e32 v179, v175
	v_lshl_add_u64 v[178:179], s[20:21], 0, v[178:179]
	v_or_b32_e32 v174, 0x120, v174
	v_lshl_add_u64 v[174:175], s[20:21], 0, v[174:175]
	s_nop 0
	v_pk_add_f32 v[188:189], v[32:33], v[172:173]
	v_pk_add_f32 v[190:191], v[30:31], v[170:171]
	s_nop 0
	v_cvt_pk_bf16_f32 v170, v190, v191
	v_cvt_pk_bf16_f32 v171, v188, v189
	global_store_dwordx2 v[178:179], v[170:171], off
	v_mov_b64_e32 v[170:171], v[196:197]
	v_mov_b64_e32 v[172:173], v[198:199]
	v_mul_f32_e32 v176, v183, v183
	v_mul_f32_e32 v177, v181, v181
	v_fmac_f32_e32 v176, v182, v182
	v_fmac_f32_e32 v177, v180, v180
	v_add_f32_e32 v176, v176, v177
	v_mul_f32_e32 v177, v187, v187
	v_mul_f32_e32 v178, v185, v185
	v_fmac_f32_e32 v177, v186, v186
	v_fmac_f32_e32 v178, v184, v184
	v_add_f32_e32 v177, v177, v178
	v_add_f32_e32 v176, v176, v177
	v_mul_f32_e32 v177, v191, v191
	v_mul_f32_e32 v178, v189, v189
	v_fmac_f32_e32 v177, v190, v190
	v_fmac_f32_e32 v178, v188, v188
	v_add_f32_e32 v177, v177, v178
	v_add_f32_e32 v178, v176, v177
	s_nop 0
	v_pk_add_f32 v[172:173], v[24:25], v[172:173]
	v_pk_add_f32 v[170:171], v[22:23], v[170:171]
	s_nop 0
	v_cvt_pk_bf16_f32 v176, v170, v171
	v_cvt_pk_bf16_f32 v177, v172, v173
	v_mul_f32_e32 v171, v171, v171
	v_mul_f32_e32 v173, v173, v173
	v_fmac_f32_e32 v171, v170, v170
	v_fmac_f32_e32 v173, v172, v172
	v_add_f32_e32 v170, v171, v173
	v_add_f32_e32 v170, v178, v170
	v_mov_b32_e32 v171, v170
	s_nop 1
	v_permlane16_swap_b32_e32 v170, v171
	v_add_f32_e32 v170, v170, v171
	v_mov_b32_e32 v171, v170
	s_nop 1
	v_permlane32_swap_b32_e32 v170, v171
	global_store_dwordx2 v[174:175], v[176:177], off
	s_and_saveexec_b64 s[58:59], s[4:5]
	s_cbranch_execz .LBB0_2151
	s_lshl_b32 s0, s12, 2
	s_or_b32 s0, s0, s74
	s_ashr_i32 s1, s0, 31
	s_lshl_b64 s[0:1], s[0:1], 15
	s_add_u32 s0, s72, s0
	s_addc_u32 s1, s73, s1
	v_add_f32_e32 v172, v170, v171
	v_lshl_add_u64 v[170:171], v[160:161], 2, s[0:1]
	global_store_dword v[170:171], v172, off offset:64
.LBB0_2151:
	s_or_b64 exec, exec, s[58:59]
	v_lshl_add_u64 v[170:171], s[56:57], 0, v[140:141]
	v_lshlrev_b64 v[170:171], 11, v[170:171]
	v_readlane_b32 s80, v254, 48
	v_lshl_add_u64 v[174:175], v[170:171], 0, v[164:165]
	v_readlane_b32 s81, v254, 49
	v_readlane_b32 s82, v254, 50
	v_readlane_b32 s83, v254, 51
	v_lshl_add_u64 v[176:177], v[174:175], 2, s[80:81]
	s_nop 4
	v_add_u32_e32 v253, 0x40000, v252
	global_load_dwordx4 v[208:211], v253, s[80:81]
	global_load_dwordx4 v[212:215], v253, s[80:81] offset:64
	global_load_dwordx4 v[216:219], v253, s[80:81] offset:512
	global_load_dwordx4 v[220:223], v253, s[80:81] offset:576
	v_add_u32_e32 v200, 0x60000, v252
	global_load_dwordx4 v[224:227], v200, s[80:81]
	global_load_dwordx4 v[228:231], v200, s[80:81] offset:64
	global_load_dwordx4 v[192:195], v200, s[80:81] offset:512
	global_load_dwordx4 v[196:199], v200, s[80:81] offset:576
	s_waitcnt vmcnt(0)
	v_mov_b64_e32 v[170:171], v[208:209]
	v_mov_b64_e32 v[172:173], v[210:211]
	v_lshlrev_b64 v[174:175], 1, v[174:175]
	v_lshl_add_u64 v[178:179], s[20:21], 0, v[174:175]
	v_readlane_b32 s84, v254, 52
	v_readlane_b32 s85, v254, 53
	v_readlane_b32 s86, v254, 54
	v_readlane_b32 s87, v254, 55
	v_readlane_b32 s88, v254, 56
	v_readlane_b32 s89, v254, 57
	v_readlane_b32 s90, v254, 58
	v_readlane_b32 s91, v254, 59
	v_readlane_b32 s92, v254, 60
	v_readlane_b32 s93, v254, 61
	v_readlane_b32 s94, v254, 62
	v_readlane_b32 s95, v254, 63
	s_nop 0
	v_pk_add_f32 v[180:181], v[52:53], v[172:173]
	v_pk_add_f32 v[182:183], v[50:51], v[170:171]
	s_nop 0
	v_cvt_pk_bf16_f32 v170, v182, v183
	v_cvt_pk_bf16_f32 v171, v180, v181
	global_store_dwordx2 v[178:179], v[170:171], off
	v_mov_b64_e32 v[170:171], v[212:213]
	v_mov_b64_e32 v[172:173], v[214:215]
	v_or_b32_e32 v178, 32, v174
	v_mov_b32_e32 v179, v175
	v_lshl_add_u64 v[178:179], s[20:21], 0, v[178:179]
	s_nop 0
	v_pk_add_f32 v[184:185], v[44:45], v[172:173]
	v_pk_add_f32 v[186:187], v[42:43], v[170:171]
	s_nop 0
	v_cvt_pk_bf16_f32 v170, v186, v187
	v_cvt_pk_bf16_f32 v171, v184, v185
	global_store_dwordx2 v[178:179], v[170:171], off
	v_mov_b64_e32 v[170:171], v[216:217]
	v_mov_b64_e32 v[172:173], v[218:219]
	v_or_b32_e32 v178, 0x100, v174
	v_mov_b32_e32 v179, v175
	v_lshl_add_u64 v[178:179], s[20:21], 0, v[178:179]
	v_or_b32_e32 v174, 0x120, v174
	v_lshl_add_u64 v[174:175], s[20:21], 0, v[174:175]
	s_nop 0
	v_pk_add_f32 v[188:189], v[16:17], v[172:173]
	v_pk_add_f32 v[190:191], v[14:15], v[170:171]
	s_nop 0
	v_cvt_pk_bf16_f32 v170, v190, v191
	v_cvt_pk_bf16_f32 v171, v188, v189
	global_store_dwordx2 v[178:179], v[170:171], off
	v_mov_b64_e32 v[170:171], v[220:221]
	v_mov_b64_e32 v[172:173], v[222:223]
	v_mul_f32_e32 v176, v183, v183
	v_mul_f32_e32 v177, v181, v181
	v_fmac_f32_e32 v176, v182, v182
	v_fmac_f32_e32 v177, v180, v180
	v_add_f32_e32 v176, v176, v177
	v_mul_f32_e32 v177, v187, v187
	v_mul_f32_e32 v178, v185, v185
	v_fmac_f32_e32 v177, v186, v186
	v_fmac_f32_e32 v178, v184, v184
	v_add_f32_e32 v177, v177, v178
	v_add_f32_e32 v176, v176, v177
	v_mul_f32_e32 v177, v191, v191
	v_mul_f32_e32 v178, v189, v189
	v_fmac_f32_e32 v177, v190, v190
	v_fmac_f32_e32 v178, v188, v188
	v_add_f32_e32 v177, v177, v178
	v_add_f32_e32 v178, v176, v177
	s_nop 0
	v_pk_add_f32 v[172:173], v[12:13], v[172:173]
	v_pk_add_f32 v[170:171], v[10:11], v[170:171]
	s_nop 0
	v_cvt_pk_bf16_f32 v176, v170, v171
	v_cvt_pk_bf16_f32 v177, v172, v173
	v_mul_f32_e32 v171, v171, v171
	v_mul_f32_e32 v173, v173, v173
	v_fmac_f32_e32 v171, v170, v170
	v_fmac_f32_e32 v173, v172, v172
	v_add_f32_e32 v170, v171, v173
	v_add_f32_e32 v170, v178, v170
	v_mov_b32_e32 v171, v170
	s_nop 1
	v_permlane16_swap_b32_e32 v170, v171
	v_add_f32_e32 v170, v170, v171
	v_mov_b32_e32 v171, v170
	s_nop 1
	v_permlane32_swap_b32_e32 v170, v171
	global_store_dwordx2 v[174:175], v[176:177], off
	s_and_saveexec_b64 s[58:59], s[4:5]
	s_cbranch_execz .LBB0_2153
	s_lshl_b32 s0, s12, 2
	s_or_b32 s0, s0, s74
	s_ashr_i32 s1, s0, 31
	s_lshl_b64 s[0:1], s[0:1], 15
	s_add_u32 s0, s72, s0
	s_addc_u32 s1, s73, s1
	v_add_f32_e32 v172, v170, v171
	v_lshl_add_u64 v[170:171], v[160:161], 2, s[0:1]
	global_store_dword v[170:171], v172, off offset:128
.LBB0_2153:
	s_or_b64 exec, exec, s[58:59]
	v_lshl_add_u64 v[170:171], s[56:57], 0, v[142:143]
	v_lshlrev_b64 v[170:171], 11, v[170:171]
	v_readlane_b32 s80, v254, 48
	v_lshl_add_u64 v[164:165], v[170:171], 0, v[164:165]
	v_readlane_b32 s81, v254, 49
	v_readlane_b32 s82, v254, 50
	v_readlane_b32 s83, v254, 51
	v_lshl_add_u64 v[174:175], v[164:165], 2, s[80:81]
	v_mov_b64_e32 v[170:171], v[224:225]
	v_mov_b64_e32 v[172:173], v[226:227]
	v_lshlrev_b64 v[164:165], 1, v[164:165]
	v_lshl_add_u64 v[176:177], s[20:21], 0, v[164:165]
	v_readlane_b32 s84, v254, 52
	v_readlane_b32 s85, v254, 53
	v_readlane_b32 s86, v254, 54
	v_readlane_b32 s87, v254, 55
	v_readlane_b32 s88, v254, 56
	v_readlane_b32 s89, v254, 57
	v_readlane_b32 s90, v254, 58
	v_readlane_b32 s91, v254, 59
	v_readlane_b32 s92, v254, 60
	v_readlane_b32 s93, v254, 61
	v_readlane_b32 s94, v254, 62
	v_readlane_b32 s95, v254, 63
	s_nop 0
	v_pk_add_f32 v[178:179], v[36:37], v[172:173]
	v_pk_add_f32 v[180:181], v[34:35], v[170:171]
	s_nop 0
	v_cvt_pk_bf16_f32 v170, v180, v181
	v_cvt_pk_bf16_f32 v171, v178, v179
	global_store_dwordx2 v[176:177], v[170:171], off
	v_mov_b64_e32 v[170:171], v[228:229]
	v_mov_b64_e32 v[172:173], v[230:231]
	v_or_b32_e32 v176, 32, v164
	v_mov_b32_e32 v177, v165
	v_lshl_add_u64 v[176:177], s[20:21], 0, v[176:177]
	s_nop 0
	v_pk_add_f32 v[182:183], v[28:29], v[172:173]
	v_pk_add_f32 v[184:185], v[26:27], v[170:171]
	s_nop 0
	v_cvt_pk_bf16_f32 v170, v184, v185
	v_cvt_pk_bf16_f32 v171, v182, v183
	global_store_dwordx2 v[176:177], v[170:171], off
	v_mov_b64_e32 v[170:171], v[192:193]
	v_mov_b64_e32 v[172:173], v[194:195]
	v_or_b32_e32 v176, 0x100, v164
	v_mov_b32_e32 v177, v165
	v_lshl_add_u64 v[176:177], s[20:21], 0, v[176:177]
	v_or_b32_e32 v164, 0x120, v164
	v_lshl_add_u64 v[164:165], s[20:21], 0, v[164:165]
	s_nop 0
	v_pk_add_f32 v[186:187], v[8:9], v[172:173]
	v_pk_add_f32 v[188:189], v[6:7], v[170:171]
	s_nop 0
	v_cvt_pk_bf16_f32 v170, v188, v189
	v_cvt_pk_bf16_f32 v171, v186, v187
	global_store_dwordx2 v[176:177], v[170:171], off
	v_mov_b64_e32 v[170:171], v[196:197]
	v_mov_b64_e32 v[172:173], v[198:199]
	v_mul_f32_e32 v174, v181, v181
	v_mul_f32_e32 v175, v179, v179
	v_fmac_f32_e32 v174, v180, v180
	v_fmac_f32_e32 v175, v178, v178
	v_add_f32_e32 v174, v174, v175
	v_mul_f32_e32 v175, v185, v185
	v_mul_f32_e32 v176, v183, v183
	v_fmac_f32_e32 v175, v184, v184
	v_fmac_f32_e32 v176, v182, v182
	v_add_f32_e32 v175, v175, v176
	v_add_f32_e32 v174, v174, v175
	v_mul_f32_e32 v175, v189, v189
	v_mul_f32_e32 v176, v187, v187
	v_fmac_f32_e32 v175, v188, v188
	v_fmac_f32_e32 v176, v186, v186
	v_add_f32_e32 v175, v175, v176
	v_add_f32_e32 v176, v174, v175
	s_nop 0
	v_pk_add_f32 v[172:173], v[4:5], v[172:173]
	v_pk_add_f32 v[170:171], v[2:3], v[170:171]
	s_nop 0
	v_cvt_pk_bf16_f32 v174, v170, v171
	v_cvt_pk_bf16_f32 v175, v172, v173
	v_mul_f32_e32 v171, v171, v171
	v_mul_f32_e32 v173, v173, v173
	v_fmac_f32_e32 v171, v170, v170
	v_fmac_f32_e32 v173, v172, v172
	global_store_dwordx2 v[164:165], v[174:175], off
	v_add_f32_e32 v164, v171, v173
	v_add_f32_e32 v164, v176, v164
	v_mov_b32_e32 v165, v164
	s_nop 1
	v_permlane16_swap_b32_e32 v164, v165
	v_add_f32_e32 v164, v164, v165
	v_mov_b32_e32 v165, v164
	s_nop 1
	v_permlane32_swap_b32_e32 v164, v165
	s_and_saveexec_b64 s[56:57], s[4:5]
	s_cbranch_execz .LBB0_2155
	s_lshl_b32 s0, s12, 2
	s_or_b32 s0, s0, s74
	s_ashr_i32 s1, s0, 31
	s_lshl_b64 s[0:1], s[0:1], 15
	s_add_u32 s0, s72, s0
	s_addc_u32 s1, s73, s1
	v_add_f32_e32 v170, v164, v165
	v_lshl_add_u64 v[164:165], v[160:161], 2, s[0:1]
	global_store_dword v[164:165], v170, off offset:192
.LBB0_2155:
	s_or_b64 exec, exec, s[56:57]
	v_readlane_b32 s80, v254, 48
	v_lshl_add_u64 v[164:165], v[162:163], 0, s[26:27]
	v_readlane_b32 s81, v254, 49
	v_readlane_b32 s82, v254, 50
	v_readlane_b32 s83, v254, 51
	v_lshl_add_u64 v[174:175], v[164:165], 2, s[80:81]
	s_nop 4
	v_add_u32_e32 v253, 0x100000, v252
	global_load_dwordx4 v[208:211], v253, s[80:81]
	global_load_dwordx4 v[212:215], v253, s[80:81] offset:64
	global_load_dwordx4 v[216:219], v253, s[80:81] offset:512
	global_load_dwordx4 v[220:223], v253, s[80:81] offset:576
	v_add_u32_e32 v200, 0x120000, v252
	global_load_dwordx4 v[224:227], v200, s[80:81]
	global_load_dwordx4 v[228:231], v200, s[80:81] offset:64
	global_load_dwordx4 v[192:195], v200, s[80:81] offset:512
	global_load_dwordx4 v[196:199], v200, s[80:81] offset:576
	s_waitcnt vmcnt(0)
	v_mov_b64_e32 v[170:171], v[208:209]
	v_mov_b64_e32 v[172:173], v[210:211]
	v_lshlrev_b64 v[164:165], 1, v[164:165]
	v_lshl_add_u64 v[176:177], s[20:21], 0, v[164:165]
	v_readlane_b32 s84, v254, 52
	v_readlane_b32 s85, v254, 53
	v_readlane_b32 s86, v254, 54
	v_readlane_b32 s87, v254, 55
	v_readlane_b32 s88, v254, 56
	v_readlane_b32 s89, v254, 57
	v_readlane_b32 s90, v254, 58
	v_readlane_b32 s91, v254, 59
	v_readlane_b32 s92, v254, 60
	v_readlane_b32 s93, v254, 61
	v_readlane_b32 s94, v254, 62
	v_readlane_b32 s95, v254, 63
	s_nop 0
	v_pk_add_f32 v[172:173], v[128:129], v[172:173]
	v_pk_add_f32 v[170:171], v[126:127], v[170:171]
	s_nop 0
	v_cvt_pk_bf16_f32 v126, v170, v171
	v_cvt_pk_bf16_f32 v127, v172, v173
	global_store_dwordx2 v[176:177], v[126:127], off
	v_mov_b64_e32 v[126:127], v[212:213]
	v_mov_b64_e32 v[128:129], v[214:215]
	v_or_b32_e32 v176, 32, v164
	v_mov_b32_e32 v177, v165
	v_lshl_add_u64 v[176:177], s[20:21], 0, v[176:177]
	v_mul_f32_e32 v171, v171, v171
	v_mul_f32_e32 v173, v173, v173
	v_fmac_f32_e32 v171, v170, v170
	v_fmac_f32_e32 v173, v172, v172
	v_add_f32_e32 v170, v171, v173
	s_nop 0
	v_pk_add_f32 v[128:129], v[124:125], v[128:129]
	v_pk_add_f32 v[126:127], v[122:123], v[126:127]
	s_nop 0
	v_cvt_pk_bf16_f32 v122, v126, v127
	v_cvt_pk_bf16_f32 v123, v128, v129
	global_store_dwordx2 v[176:177], v[122:123], off
	v_mov_b64_e32 v[122:123], v[216:217]
	v_mov_b64_e32 v[124:125], v[218:219]
	v_or_b32_e32 v176, 0x100, v164
	v_mov_b32_e32 v177, v165
	v_lshl_add_u64 v[176:177], s[20:21], 0, v[176:177]
	v_mul_f32_e32 v127, v127, v127
	v_mul_f32_e32 v129, v129, v129
	v_fmac_f32_e32 v127, v126, v126
	v_fmac_f32_e32 v129, v128, v128
	v_add_f32_e32 v126, v127, v129
	v_add_f32_e32 v126, v170, v126
	v_or_b32_e32 v164, 0x120, v164
	v_lshl_add_u64 v[164:165], s[20:21], 0, v[164:165]
	s_nop 0
	v_pk_add_f32 v[124:125], v[120:121], v[124:125]
	v_pk_add_f32 v[122:123], v[118:119], v[122:123]
	s_nop 0
	v_cvt_pk_bf16_f32 v118, v122, v123
	v_cvt_pk_bf16_f32 v119, v124, v125
	global_store_dwordx2 v[176:177], v[118:119], off
	v_mov_b64_e32 v[118:119], v[220:221]
	v_mov_b64_e32 v[120:121], v[222:223]
	v_mul_f32_e32 v123, v123, v123
	v_mul_f32_e32 v125, v125, v125
	v_fmac_f32_e32 v123, v122, v122
	v_fmac_f32_e32 v125, v124, v124
	v_add_f32_e32 v122, v123, v125
	v_add_f32_e32 v122, v126, v122
	s_nop 0
	v_pk_add_f32 v[116:117], v[116:117], v[120:121]
	v_pk_add_f32 v[114:115], v[114:115], v[118:119]
	s_nop 0
	v_cvt_pk_bf16_f32 v118, v114, v115
	v_cvt_pk_bf16_f32 v119, v116, v117
	v_mul_f32_e32 v115, v115, v115
	v_mul_f32_e32 v117, v117, v117
	v_fmac_f32_e32 v115, v114, v114
	v_fmac_f32_e32 v117, v116, v116
	v_add_f32_e32 v114, v115, v117
	v_add_f32_e32 v114, v122, v114
	v_mov_b32_e32 v115, v114
	s_nop 1
	v_permlane16_swap_b32_e32 v114, v115
	v_add_f32_e32 v114, v114, v115
	v_mov_b32_e32 v115, v114
	s_nop 1
	v_permlane32_swap_b32_e32 v114, v115
	global_store_dwordx2 v[164:165], v[118:119], off
	s_and_saveexec_b64 s[56:57], s[4:5]
	s_cbranch_execz .LBB0_2157
	s_lshl_b32 s0, s12, 2
	s_or_b32 s0, s0, s74
	s_ashr_i32 s1, s0, 31
	s_lshl_b64 s[0:1], s[0:1], 15
	s_add_u32 s0, s72, s0
	s_addc_u32 s1, s73, s1
	v_add_f32_e32 v116, v114, v115
	v_lshl_add_u64 v[114:115], v[160:161], 2, s[0:1]
	global_store_dword v[114:115], v116, off offset:512
.LBB0_2157:
	s_or_b64 exec, exec, s[56:57]
	v_readlane_b32 s80, v254, 48
	v_lshl_add_u64 v[118:119], v[162:163], 0, s[28:29]
	v_readlane_b32 s81, v254, 49
	v_readlane_b32 s82, v254, 50
	v_readlane_b32 s83, v254, 51
	v_lshl_add_u64 v[120:121], v[118:119], 2, s[80:81]
	v_mov_b64_e32 v[114:115], v[224:225]
	v_mov_b64_e32 v[116:117], v[226:227]
	v_lshlrev_b64 v[118:119], 1, v[118:119]
	v_lshl_add_u64 v[122:123], s[20:21], 0, v[118:119]
	v_readlane_b32 s84, v254, 52
	v_readlane_b32 s85, v254, 53
	v_readlane_b32 s86, v254, 54
	v_readlane_b32 s87, v254, 55
	v_readlane_b32 s88, v254, 56
	v_readlane_b32 s89, v254, 57
	v_readlane_b32 s90, v254, 58
	v_readlane_b32 s91, v254, 59
	v_readlane_b32 s92, v254, 60
	v_readlane_b32 s93, v254, 61
	v_readlane_b32 s94, v254, 62
	v_readlane_b32 s95, v254, 63
	s_nop 0
	v_pk_add_f32 v[116:117], v[112:113], v[116:117]
	v_pk_add_f32 v[114:115], v[110:111], v[114:115]
	s_nop 0
	v_cvt_pk_bf16_f32 v110, v114, v115
	v_cvt_pk_bf16_f32 v111, v116, v117
	global_store_dwordx2 v[122:123], v[110:111], off
	v_mov_b64_e32 v[110:111], v[228:229]
	v_mov_b64_e32 v[112:113], v[230:231]
	v_or_b32_e32 v122, 32, v118
	v_mov_b32_e32 v123, v119
	v_lshl_add_u64 v[122:123], s[20:21], 0, v[122:123]
	v_mul_f32_e32 v115, v115, v115
	v_mul_f32_e32 v117, v117, v117
	v_fmac_f32_e32 v115, v114, v114
	v_fmac_f32_e32 v117, v116, v116
	v_add_f32_e32 v114, v115, v117
	s_nop 0
	v_pk_add_f32 v[112:113], v[108:109], v[112:113]
	v_pk_add_f32 v[110:111], v[106:107], v[110:111]
	s_nop 0
	v_cvt_pk_bf16_f32 v106, v110, v111
	v_cvt_pk_bf16_f32 v107, v112, v113
	global_store_dwordx2 v[122:123], v[106:107], off
	v_mov_b64_e32 v[106:107], v[192:193]
	v_mov_b64_e32 v[108:109], v[194:195]
	v_or_b32_e32 v122, 0x100, v118
	v_mov_b32_e32 v123, v119
	v_lshl_add_u64 v[122:123], s[20:21], 0, v[122:123]
	v_mul_f32_e32 v111, v111, v111
	v_mul_f32_e32 v113, v113, v113
	v_fmac_f32_e32 v111, v110, v110
	v_fmac_f32_e32 v113, v112, v112
	v_add_f32_e32 v110, v111, v113
	v_add_f32_e32 v110, v114, v110
	v_or_b32_e32 v118, 0x120, v118
	v_lshl_add_u64 v[118:119], s[20:21], 0, v[118:119]
	s_nop 0
	v_pk_add_f32 v[108:109], v[104:105], v[108:109]
	v_pk_add_f32 v[106:107], v[102:103], v[106:107]
	s_nop 0
	v_cvt_pk_bf16_f32 v102, v106, v107
	v_cvt_pk_bf16_f32 v103, v108, v109
	global_store_dwordx2 v[122:123], v[102:103], off
	v_mov_b64_e32 v[102:103], v[196:197]
	v_mov_b64_e32 v[104:105], v[198:199]
	v_mul_f32_e32 v107, v107, v107
	v_mul_f32_e32 v109, v109, v109
	v_fmac_f32_e32 v107, v106, v106
	v_fmac_f32_e32 v109, v108, v108
	v_add_f32_e32 v106, v107, v109
	v_add_f32_e32 v106, v110, v106
	s_nop 0
	v_pk_add_f32 v[100:101], v[100:101], v[104:105]
	v_pk_add_f32 v[98:99], v[98:99], v[102:103]
	s_nop 0
	v_cvt_pk_bf16_f32 v102, v98, v99
	v_cvt_pk_bf16_f32 v103, v100, v101
	v_mul_f32_e32 v99, v99, v99
	v_mul_f32_e32 v101, v101, v101
	v_fmac_f32_e32 v99, v98, v98
	v_fmac_f32_e32 v101, v100, v100
	v_add_f32_e32 v98, v99, v101
	v_add_f32_e32 v98, v106, v98
	v_mov_b32_e32 v99, v98
	s_nop 1
	v_permlane16_swap_b32_e32 v98, v99
	v_add_f32_e32 v98, v98, v99
	v_mov_b32_e32 v99, v98
	s_nop 1
	v_permlane32_swap_b32_e32 v98, v99
	global_store_dwordx2 v[118:119], v[102:103], off
	s_and_saveexec_b64 s[56:57], s[4:5]
	s_cbranch_execz .LBB0_2159
	s_lshl_b32 s0, s12, 2
	s_or_b32 s0, s0, s74
	s_ashr_i32 s1, s0, 31
	s_lshl_b64 s[0:1], s[0:1], 15
	s_add_u32 s0, s72, s0
	s_addc_u32 s1, s73, s1
	v_add_f32_e32 v100, v98, v99
	v_lshl_add_u64 v[98:99], v[160:161], 2, s[0:1]
	global_store_dword v[98:99], v100, off offset:576
.LBB0_2159:
	s_or_b64 exec, exec, s[56:57]
	v_readlane_b32 s80, v254, 48
	v_lshl_add_u64 v[102:103], v[162:163], 0, s[30:31]
	v_readlane_b32 s81, v254, 49
	v_readlane_b32 s82, v254, 50
	v_readlane_b32 s83, v254, 51
	v_lshl_add_u64 v[104:105], v[102:103], 2, s[80:81]
	s_nop 4
	v_add_u32_e32 v253, 0x140000, v252
	global_load_dwordx4 v[208:211], v253, s[80:81]
	global_load_dwordx4 v[212:215], v253, s[80:81] offset:64
	global_load_dwordx4 v[216:219], v253, s[80:81] offset:512
	global_load_dwordx4 v[220:223], v253, s[80:81] offset:576
	v_add_u32_e32 v200, 0x160000, v252
	global_load_dwordx4 v[224:227], v200, s[80:81]
	global_load_dwordx4 v[228:231], v200, s[80:81] offset:64
	global_load_dwordx4 v[192:195], v200, s[80:81] offset:512
	global_load_dwordx4 v[196:199], v200, s[80:81] offset:576
	s_waitcnt vmcnt(0)
	v_mov_b64_e32 v[98:99], v[208:209]
	v_mov_b64_e32 v[100:101], v[210:211]
	v_lshlrev_b64 v[102:103], 1, v[102:103]
	v_lshl_add_u64 v[106:107], s[20:21], 0, v[102:103]
	v_readlane_b32 s84, v254, 52
	v_readlane_b32 s85, v254, 53
	v_readlane_b32 s86, v254, 54
	v_readlane_b32 s87, v254, 55
	v_readlane_b32 s88, v254, 56
	v_readlane_b32 s89, v254, 57
	v_readlane_b32 s90, v254, 58
	v_readlane_b32 s91, v254, 59
	v_readlane_b32 s92, v254, 60
	v_readlane_b32 s93, v254, 61
	v_readlane_b32 s94, v254, 62
	v_readlane_b32 s95, v254, 63
	s_nop 0
	v_pk_add_f32 v[100:101], v[96:97], v[100:101]
	v_pk_add_f32 v[98:99], v[94:95], v[98:99]
	s_nop 0
	v_cvt_pk_bf16_f32 v94, v98, v99
	v_cvt_pk_bf16_f32 v95, v100, v101
	global_store_dwordx2 v[106:107], v[94:95], off
	v_mov_b64_e32 v[94:95], v[212:213]
	v_mov_b64_e32 v[96:97], v[214:215]
	v_or_b32_e32 v106, 32, v102
	v_mov_b32_e32 v107, v103
	v_lshl_add_u64 v[106:107], s[20:21], 0, v[106:107]
	v_mul_f32_e32 v99, v99, v99
	v_mul_f32_e32 v101, v101, v101
	v_fmac_f32_e32 v99, v98, v98
	v_fmac_f32_e32 v101, v100, v100
	v_add_f32_e32 v98, v99, v101
	s_nop 0
	v_pk_add_f32 v[96:97], v[92:93], v[96:97]
	v_pk_add_f32 v[94:95], v[90:91], v[94:95]
	s_nop 0
	v_cvt_pk_bf16_f32 v90, v94, v95
	v_cvt_pk_bf16_f32 v91, v96, v97
	global_store_dwordx2 v[106:107], v[90:91], off
	v_mov_b64_e32 v[90:91], v[216:217]
	v_mov_b64_e32 v[92:93], v[218:219]
	v_or_b32_e32 v106, 0x100, v102
	v_mov_b32_e32 v107, v103
	v_lshl_add_u64 v[106:107], s[20:21], 0, v[106:107]
	v_mul_f32_e32 v95, v95, v95
	v_mul_f32_e32 v97, v97, v97
	v_fmac_f32_e32 v95, v94, v94
	v_fmac_f32_e32 v97, v96, v96
	v_add_f32_e32 v94, v95, v97
	v_add_f32_e32 v94, v98, v94
	v_or_b32_e32 v102, 0x120, v102
	v_lshl_add_u64 v[102:103], s[20:21], 0, v[102:103]
	s_nop 0
	v_pk_add_f32 v[92:93], v[88:89], v[92:93]
	v_pk_add_f32 v[90:91], v[86:87], v[90:91]
	s_nop 0
	v_cvt_pk_bf16_f32 v86, v90, v91
	v_cvt_pk_bf16_f32 v87, v92, v93
	global_store_dwordx2 v[106:107], v[86:87], off
	v_mov_b64_e32 v[86:87], v[220:221]
	v_mov_b64_e32 v[88:89], v[222:223]
	v_mul_f32_e32 v91, v91, v91
	v_mul_f32_e32 v93, v93, v93
	v_fmac_f32_e32 v91, v90, v90
	v_fmac_f32_e32 v93, v92, v92
	v_add_f32_e32 v90, v91, v93
	v_add_f32_e32 v90, v94, v90
	s_nop 0
	v_pk_add_f32 v[84:85], v[84:85], v[88:89]
	v_pk_add_f32 v[82:83], v[82:83], v[86:87]
	s_nop 0
	v_cvt_pk_bf16_f32 v86, v82, v83
	v_cvt_pk_bf16_f32 v87, v84, v85
	v_mul_f32_e32 v83, v83, v83
	v_mul_f32_e32 v85, v85, v85
	v_fmac_f32_e32 v83, v82, v82
	v_fmac_f32_e32 v85, v84, v84
	v_add_f32_e32 v82, v83, v85
	v_add_f32_e32 v82, v90, v82
	v_mov_b32_e32 v83, v82
	s_nop 1
	v_permlane16_swap_b32_e32 v82, v83
	v_add_f32_e32 v82, v82, v83
	v_mov_b32_e32 v83, v82
	s_nop 1
	v_permlane32_swap_b32_e32 v82, v83
	global_store_dwordx2 v[102:103], v[86:87], off
	s_and_saveexec_b64 s[56:57], s[4:5]
	s_cbranch_execz .LBB0_2161
	s_lshl_b32 s0, s12, 2
	s_or_b32 s0, s0, s74
	s_ashr_i32 s1, s0, 31
	s_lshl_b64 s[0:1], s[0:1], 15
	s_add_u32 s0, s72, s0
	s_addc_u32 s1, s73, s1
	v_add_f32_e32 v84, v82, v83
	v_lshl_add_u64 v[82:83], v[160:161], 2, s[0:1]
	global_store_dword v[82:83], v84, off offset:640
.LBB0_2161:
	s_or_b64 exec, exec, s[56:57]
	v_readlane_b32 s80, v254, 48
	v_lshl_add_u64 v[86:87], v[162:163], 0, s[34:35]
	v_readlane_b32 s81, v254, 49
	v_readlane_b32 s82, v254, 50
	v_readlane_b32 s83, v254, 51
	v_lshl_add_u64 v[88:89], v[86:87], 2, s[80:81]
	v_mov_b64_e32 v[82:83], v[224:225]
	v_mov_b64_e32 v[84:85], v[226:227]
	v_lshlrev_b64 v[86:87], 1, v[86:87]
	v_lshl_add_u64 v[90:91], s[20:21], 0, v[86:87]
	v_readlane_b32 s84, v254, 52
	v_readlane_b32 s85, v254, 53
	v_readlane_b32 s86, v254, 54
	v_readlane_b32 s87, v254, 55
	v_readlane_b32 s88, v254, 56
	v_readlane_b32 s89, v254, 57
	v_readlane_b32 s90, v254, 58
	v_readlane_b32 s91, v254, 59
	v_readlane_b32 s92, v254, 60
	v_readlane_b32 s93, v254, 61
	v_readlane_b32 s94, v254, 62
	v_readlane_b32 s95, v254, 63
	s_nop 0
	v_pk_add_f32 v[84:85], v[80:81], v[84:85]
	v_pk_add_f32 v[82:83], v[78:79], v[82:83]
	s_nop 0
	v_cvt_pk_bf16_f32 v78, v82, v83
	v_cvt_pk_bf16_f32 v79, v84, v85
	global_store_dwordx2 v[90:91], v[78:79], off
	v_mov_b64_e32 v[78:79], v[228:229]
	v_mov_b64_e32 v[80:81], v[230:231]
	v_or_b32_e32 v90, 32, v86
	v_mov_b32_e32 v91, v87
	v_lshl_add_u64 v[90:91], s[20:21], 0, v[90:91]
	v_mul_f32_e32 v83, v83, v83
	v_mul_f32_e32 v85, v85, v85
	v_fmac_f32_e32 v83, v82, v82
	v_fmac_f32_e32 v85, v84, v84
	v_add_f32_e32 v82, v83, v85
	s_nop 0
	v_pk_add_f32 v[80:81], v[76:77], v[80:81]
	v_pk_add_f32 v[78:79], v[74:75], v[78:79]
	s_nop 0
	v_cvt_pk_bf16_f32 v74, v78, v79
	v_cvt_pk_bf16_f32 v75, v80, v81
	global_store_dwordx2 v[90:91], v[74:75], off
	v_mov_b64_e32 v[74:75], v[192:193]
	v_mov_b64_e32 v[76:77], v[194:195]
	v_or_b32_e32 v90, 0x100, v86
	v_mov_b32_e32 v91, v87
	v_lshl_add_u64 v[90:91], s[20:21], 0, v[90:91]
	v_mul_f32_e32 v79, v79, v79
	v_mul_f32_e32 v81, v81, v81
	v_fmac_f32_e32 v79, v78, v78
	v_fmac_f32_e32 v81, v80, v80
	v_add_f32_e32 v78, v79, v81
	v_add_f32_e32 v78, v82, v78
	v_or_b32_e32 v86, 0x120, v86
	v_lshl_add_u64 v[86:87], s[20:21], 0, v[86:87]
	s_nop 0
	v_pk_add_f32 v[76:77], v[72:73], v[76:77]
	v_pk_add_f32 v[74:75], v[70:71], v[74:75]
	s_nop 0
	v_cvt_pk_bf16_f32 v70, v74, v75
	v_cvt_pk_bf16_f32 v71, v76, v77
	global_store_dwordx2 v[90:91], v[70:71], off
	v_mov_b64_e32 v[70:71], v[196:197]
	v_mov_b64_e32 v[72:73], v[198:199]
	v_mul_f32_e32 v75, v75, v75
	v_mul_f32_e32 v77, v77, v77
	v_fmac_f32_e32 v75, v74, v74
	v_fmac_f32_e32 v77, v76, v76
	v_add_f32_e32 v74, v75, v77
	v_add_f32_e32 v74, v78, v74
	s_nop 0
	v_pk_add_f32 v[20:21], v[20:21], v[72:73]
	v_pk_add_f32 v[18:19], v[18:19], v[70:71]
	s_nop 0
	v_cvt_pk_bf16_f32 v70, v18, v19
	v_cvt_pk_bf16_f32 v71, v20, v21
	v_mul_f32_e32 v19, v19, v19
	v_mul_f32_e32 v21, v21, v21
	v_fmac_f32_e32 v19, v18, v18
	v_fmac_f32_e32 v21, v20, v20
	v_add_f32_e32 v18, v19, v21
	v_add_f32_e32 v18, v74, v18
	v_mov_b32_e32 v19, v18
	s_nop 1
	v_permlane16_swap_b32_e32 v18, v19
	v_add_f32_e32 v18, v18, v19
	v_mov_b32_e32 v19, v18
	s_nop 1
	v_permlane32_swap_b32_e32 v18, v19
	global_store_dwordx2 v[86:87], v[70:71], off
	s_and_saveexec_b64 s[56:57], s[4:5]
	s_cbranch_execz .LBB0_2163
	s_lshl_b32 s0, s12, 2
	s_or_b32 s0, s0, s74
	s_ashr_i32 s1, s0, 31
	s_lshl_b64 s[0:1], s[0:1], 15
	s_add_u32 s0, s72, s0
	s_addc_u32 s1, s73, s1
	v_add_f32_e32 v20, v18, v19
	v_lshl_add_u64 v[18:19], v[160:161], 2, s[0:1]
	global_store_dword v[18:19], v20, off offset:704

.LBB0_2544:
	s_nop 15
	s_nop 15
	s_cmp_lt_i32 s58, 32
	s_mov_b64 s[60:61], -1
	s_cbranch_scc0 .LBB0_2563
	s_ashr_i32 s59, s58, 31
	s_lshl_b64 s[58:59], s[58:59], 8
	v_lshl_or_b32 v164, s10, 8, v172
	v_lshl_add_u64 v[160:161], s[58:59], 0, v[136:137]
	v_ashrrev_i32_e32 v165, 31, v164
	v_lshlrev_b64 v[162:163], 11, v[160:161]
	v_lshl_add_u64 v[162:163], v[162:163], 0, v[164:165]
	v_lshlrev_b64 v[162:163], 1, v[162:163]
	v_lshl_add_u64 v[166:167], s[18:19], 0, v[162:163]
	v_mov_b32_e32 v198, v162
	global_load_dwordx2 v[208:209], v198, s[18:19]
	global_load_dwordx2 v[210:211], v198, s[18:19] offset:32
	global_load_dwordx2 v[212:213], v198, s[18:19] offset:256
	global_load_dwordx2 v[214:215], v198, s[18:19] offset:288
	v_add_u32_e32 v200, 0x10000, v198
	global_load_dwordx2 v[216:217], v200, s[18:19]
	global_load_dwordx2 v[218:219], v200, s[18:19] offset:32
	global_load_dwordx2 v[220:221], v200, s[18:19] offset:256
	global_load_dwordx2 v[222:223], v200, s[18:19] offset:288
	v_add_u32_e32 v201, 0x20000, v198
	global_load_dwordx2 v[224:225], v201, s[18:19]
	global_load_dwordx2 v[226:227], v201, s[18:19] offset:32
	global_load_dwordx2 v[228:229], v201, s[18:19] offset:256
	global_load_dwordx2 v[230:231], v201, s[18:19] offset:288
	v_add_u32_e32 v202, 0x30000, v198
	global_load_dwordx2 v[190:191], v202, s[18:19]
	global_load_dwordx2 v[192:193], v202, s[18:19] offset:32
	global_load_dwordx2 v[194:195], v202, s[18:19] offset:256
	global_load_dwordx2 v[196:197], v202, s[18:19] offset:288
	s_waitcnt vmcnt(0)
	v_mov_b64_e32 v[166:167], v[208:209]
	v_or_b32_e32 v170, 32, v162
	v_mov_b32_e32 v171, v163
	v_lshl_add_u64 v[176:177], s[18:19], 0, v[170:171]
	v_lshl_add_u64 v[180:181], s[20:21], 0, v[162:163]
	v_or_b32_e32 v182, 0x100, v162
	v_mov_b32_e32 v183, v163
	v_lshl_add_u64 v[184:185], s[18:19], 0, v[182:183]
	v_or_b32_e32 v186, 0x120, v162
	v_mov_b32_e32 v187, v163
	v_lshl_add_u64 v[170:171], s[20:21], 0, v[170:171]
	v_lshl_add_u64 v[188:189], s[18:19], 0, v[186:187]
	v_lshl_add_u64 v[182:183], s[20:21], 0, v[182:183]
	v_lshl_add_u64 v[186:187], s[20:21], 0, v[186:187]
	s_nop 0
	v_lshlrev_b32_e32 v168, 16, v166
	v_and_b32_e32 v169, 0xffff0000, v166
	v_lshlrev_b32_e32 v166, 16, v167
	v_and_b32_e32 v167, 0xffff0000, v167
	v_pk_add_f32 v[166:167], v[68:69], v[166:167]
	v_pk_add_f32 v[168:169], v[66:67], v[168:169]
	s_nop 0
	v_cvt_pk_bf16_f32 v178, v168, v169
	v_cvt_pk_bf16_f32 v179, v166, v167
	v_mov_b64_e32 v[176:177], v[210:211]
	v_mul_f32_e32 v169, v169, v169
	global_store_dwordx2 v[180:181], v[178:179], off
	v_mul_f32_e32 v167, v167, v167
	v_fmac_f32_e32 v169, v168, v168
	v_fmac_f32_e32 v167, v166, v166
	v_add_f32_e32 v166, v169, v167
	s_nop 0
	v_lshlrev_b32_e32 v178, 16, v176
	v_and_b32_e32 v179, 0xffff0000, v176
	v_lshlrev_b32_e32 v176, 16, v177
	v_and_b32_e32 v177, 0xffff0000, v177
	v_pk_add_f32 v[176:177], v[64:65], v[176:177]
	v_pk_add_f32 v[178:179], v[62:63], v[178:179]
	v_mul_f32_e32 v168, v177, v177
	v_cvt_pk_bf16_f32 v180, v178, v179
	v_cvt_pk_bf16_f32 v181, v176, v177
	v_mov_b64_e32 v[184:185], v[212:213]
	v_mul_f32_e32 v167, v179, v179
	global_store_dwordx2 v[170:171], v[180:181], off
	v_fmac_f32_e32 v167, v178, v178
	v_fmac_f32_e32 v168, v176, v176
	v_add_f32_e32 v167, v167, v168
	v_add_f32_e32 v166, v166, v167
	s_nop 0
	v_lshlrev_b32_e32 v170, 16, v184
	v_and_b32_e32 v171, 0xffff0000, v184
	v_lshlrev_b32_e32 v180, 16, v185
	v_and_b32_e32 v181, 0xffff0000, v185
	v_pk_add_f32 v[180:181], v[48:49], v[180:181]
	v_pk_add_f32 v[170:171], v[46:47], v[170:171]
	v_mul_f32_e32 v168, v181, v181
	v_cvt_pk_bf16_f32 v184, v170, v171
	v_cvt_pk_bf16_f32 v185, v180, v181
	v_mov_b64_e32 v[188:189], v[214:215]
	v_mul_f32_e32 v167, v171, v171
	v_fmac_f32_e32 v167, v170, v170
	v_fmac_f32_e32 v168, v180, v180
	v_add_f32_e32 v167, v167, v168
	v_add_f32_e32 v176, v166, v167
	global_store_dwordx2 v[182:183], v[184:185], off
	s_nop 0
	v_lshlrev_b32_e32 v166, 16, v188
	v_and_b32_e32 v167, 0xffff0000, v188
	v_lshlrev_b32_e32 v168, 16, v189
	v_and_b32_e32 v169, 0xffff0000, v189
	v_pk_add_f32 v[168:169], v[40:41], v[168:169]
	v_pk_add_f32 v[166:167], v[38:39], v[166:167]
	s_nop 0
	v_cvt_pk_bf16_f32 v170, v166, v167
	v_cvt_pk_bf16_f32 v171, v168, v169
	v_mul_f32_e32 v167, v167, v167
	v_mul_f32_e32 v169, v169, v169
	v_fmac_f32_e32 v167, v166, v166
	v_fmac_f32_e32 v169, v168, v168
	v_add_f32_e32 v166, v167, v169
	v_add_f32_e32 v166, v176, v166
	v_mov_b32_e32 v167, v166
	s_nop 1
	v_permlane16_swap_b32_e32 v166, v167
	v_add_f32_e32 v166, v166, v167
	v_mov_b32_e32 v167, v166
	s_nop 1
	v_permlane32_swap_b32_e32 v166, v167
	global_store_dwordx2 v[186:187], v[170:171], off
	s_and_saveexec_b64 s[60:61], s[4:5]
	s_cbranch_execz .LBB0_2547
	s_lshl_b32 s0, s10, 2
	s_or_b32 s0, s0, s76
	s_ashr_i32 s1, s0, 31
	s_lshl_b64 s[0:1], s[0:1], 15
	s_add_u32 s0, s72, s0
	s_addc_u32 s1, s73, s1
	v_add_f32_e32 v168, v166, v167
	v_lshl_add_u64 v[166:167], v[160:161], 2, s[0:1]
	global_store_dword v[166:167], v168, off
.LBB0_2547:
	s_or_b64 exec, exec, s[60:61]
	v_lshl_add_u64 v[166:167], s[58:59], 0, v[138:139]
	v_lshlrev_b64 v[166:167], 11, v[166:167]
	v_lshl_add_u64 v[166:167], v[166:167], 0, v[164:165]
	v_lshlrev_b64 v[166:167], 1, v[166:167]
	v_lshl_add_u64 v[168:169], s[18:19], 0, v[166:167]
	v_mov_b64_e32 v[168:169], v[216:217]
	v_or_b32_e32 v176, 32, v166
	v_mov_b32_e32 v177, v167
	v_lshl_add_u64 v[178:179], s[18:19], 0, v[176:177]
	v_lshl_add_u64 v[182:183], s[20:21], 0, v[166:167]
	v_or_b32_e32 v184, 0x100, v166
	v_mov_b32_e32 v185, v167
	v_lshl_add_u64 v[186:187], s[18:19], 0, v[184:185]
	v_or_b32_e32 v166, 0x120, v166
	v_lshl_add_u64 v[176:177], s[20:21], 0, v[176:177]
	v_lshl_add_u64 v[188:189], s[18:19], 0, v[166:167]
	v_lshl_add_u64 v[184:185], s[20:21], 0, v[184:185]
	v_lshl_add_u64 v[166:167], s[20:21], 0, v[166:167]
	s_nop 0
	v_lshlrev_b32_e32 v170, 16, v168
	v_and_b32_e32 v171, 0xffff0000, v168
	v_lshlrev_b32_e32 v168, 16, v169
	v_and_b32_e32 v169, 0xffff0000, v169
	v_pk_add_f32 v[168:169], v[60:61], v[168:169]
	v_pk_add_f32 v[170:171], v[58:59], v[170:171]
	s_nop 0
	v_cvt_pk_bf16_f32 v180, v170, v171
	v_cvt_pk_bf16_f32 v181, v168, v169
	v_mov_b64_e32 v[178:179], v[218:219]
	v_mul_f32_e32 v171, v171, v171
	global_store_dwordx2 v[182:183], v[180:181], off
	v_mul_f32_e32 v169, v169, v169
	v_fmac_f32_e32 v171, v170, v170
	v_fmac_f32_e32 v169, v168, v168
	v_add_f32_e32 v168, v171, v169
	s_nop 0
	v_lshlrev_b32_e32 v180, 16, v178
	v_and_b32_e32 v181, 0xffff0000, v178
	v_lshlrev_b32_e32 v178, 16, v179
	v_and_b32_e32 v179, 0xffff0000, v179
	v_pk_add_f32 v[178:179], v[56:57], v[178:179]
	v_pk_add_f32 v[180:181], v[54:55], v[180:181]
	v_mul_f32_e32 v170, v179, v179
	v_cvt_pk_bf16_f32 v182, v180, v181
	v_cvt_pk_bf16_f32 v183, v178, v179
	v_mov_b64_e32 v[186:187], v[220:221]
	v_mul_f32_e32 v169, v181, v181
	global_store_dwordx2 v[176:177], v[182:183], off
	v_fmac_f32_e32 v169, v180, v180
	v_fmac_f32_e32 v170, v178, v178
	v_add_f32_e32 v169, v169, v170
	v_add_f32_e32 v168, v168, v169
	s_nop 0
	v_lshlrev_b32_e32 v176, 16, v186
	v_and_b32_e32 v177, 0xffff0000, v186
	v_lshlrev_b32_e32 v182, 16, v187
	v_and_b32_e32 v183, 0xffff0000, v187
	v_pk_add_f32 v[182:183], v[32:33], v[182:183]
	v_pk_add_f32 v[176:177], v[30:31], v[176:177]
	v_mul_f32_e32 v170, v183, v183
	v_cvt_pk_bf16_f32 v186, v176, v177
	v_cvt_pk_bf16_f32 v187, v182, v183
	v_mov_b64_e32 v[188:189], v[222:223]
	v_mul_f32_e32 v169, v177, v177
	v_fmac_f32_e32 v169, v176, v176
	v_fmac_f32_e32 v170, v182, v182
	v_add_f32_e32 v169, v169, v170
	v_add_f32_e32 v178, v168, v169
	global_store_dwordx2 v[184:185], v[186:187], off
	s_nop 0
	v_lshlrev_b32_e32 v168, 16, v188
	v_and_b32_e32 v169, 0xffff0000, v188
	v_lshlrev_b32_e32 v170, 16, v189
	v_and_b32_e32 v171, 0xffff0000, v189
	v_pk_add_f32 v[170:171], v[24:25], v[170:171]
	v_pk_add_f32 v[168:169], v[22:23], v[168:169]
	s_nop 0
	v_cvt_pk_bf16_f32 v176, v168, v169
	v_cvt_pk_bf16_f32 v177, v170, v171
	v_mul_f32_e32 v169, v169, v169
	v_mul_f32_e32 v171, v171, v171
	v_fmac_f32_e32 v169, v168, v168
	v_fmac_f32_e32 v171, v170, v170
	global_store_dwordx2 v[166:167], v[176:177], off
	v_add_f32_e32 v166, v169, v171
	v_add_f32_e32 v166, v178, v166
	v_mov_b32_e32 v167, v166
	s_nop 1
	v_permlane16_swap_b32_e32 v166, v167
	v_add_f32_e32 v166, v166, v167
	v_mov_b32_e32 v167, v166
	s_nop 1
	v_permlane32_swap_b32_e32 v166, v167
	s_and_saveexec_b64 s[60:61], s[4:5]
	s_cbranch_execz .LBB0_2549
	s_lshl_b32 s0, s10, 2
	s_or_b32 s0, s0, s76
	s_ashr_i32 s1, s0, 31
	s_lshl_b64 s[0:1], s[0:1], 15
	s_add_u32 s0, s72, s0
	s_addc_u32 s1, s73, s1
	v_add_f32_e32 v168, v166, v167
	v_lshl_add_u64 v[166:167], v[160:161], 2, s[0:1]
	global_store_dword v[166:167], v168, off offset:64
.LBB0_2549:
	s_or_b64 exec, exec, s[60:61]
	v_lshl_add_u64 v[166:167], s[58:59], 0, v[140:141]
	v_lshlrev_b64 v[166:167], 11, v[166:167]
	v_lshl_add_u64 v[166:167], v[166:167], 0, v[164:165]
	v_lshlrev_b64 v[166:167], 1, v[166:167]
	v_lshl_add_u64 v[168:169], s[18:19], 0, v[166:167]
	v_mov_b64_e32 v[168:169], v[224:225]
	v_or_b32_e32 v176, 32, v166
	v_mov_b32_e32 v177, v167
	v_lshl_add_u64 v[178:179], s[18:19], 0, v[176:177]
	v_lshl_add_u64 v[182:183], s[20:21], 0, v[166:167]
	v_or_b32_e32 v184, 0x100, v166
	v_mov_b32_e32 v185, v167
	v_lshl_add_u64 v[186:187], s[18:19], 0, v[184:185]
	v_or_b32_e32 v166, 0x120, v166
	v_lshl_add_u64 v[176:177], s[20:21], 0, v[176:177]
	v_lshl_add_u64 v[188:189], s[18:19], 0, v[166:167]
	v_lshl_add_u64 v[184:185], s[20:21], 0, v[184:185]
	v_lshl_add_u64 v[166:167], s[20:21], 0, v[166:167]
	s_nop 0
	v_lshlrev_b32_e32 v170, 16, v168
	v_and_b32_e32 v171, 0xffff0000, v168
	v_lshlrev_b32_e32 v168, 16, v169
	v_and_b32_e32 v169, 0xffff0000, v169
	v_pk_add_f32 v[168:169], v[52:53], v[168:169]
	v_pk_add_f32 v[170:171], v[50:51], v[170:171]
	s_nop 0
	v_cvt_pk_bf16_f32 v180, v170, v171
	v_cvt_pk_bf16_f32 v181, v168, v169
	v_mov_b64_e32 v[178:179], v[226:227]
	v_mul_f32_e32 v171, v171, v171
	global_store_dwordx2 v[182:183], v[180:181], off
	v_mul_f32_e32 v169, v169, v169
	v_fmac_f32_e32 v171, v170, v170
	v_fmac_f32_e32 v169, v168, v168
	v_add_f32_e32 v168, v171, v169
	s_nop 0
	v_lshlrev_b32_e32 v180, 16, v178
	v_and_b32_e32 v181, 0xffff0000, v178
	v_lshlrev_b32_e32 v178, 16, v179
	v_and_b32_e32 v179, 0xffff0000, v179
	v_pk_add_f32 v[178:179], v[44:45], v[178:179]
	v_pk_add_f32 v[180:181], v[42:43], v[180:181]
	v_mul_f32_e32 v170, v179, v179
	v_cvt_pk_bf16_f32 v182, v180, v181
	v_cvt_pk_bf16_f32 v183, v178, v179
	v_mov_b64_e32 v[186:187], v[228:229]
	v_mul_f32_e32 v169, v181, v181
	global_store_dwordx2 v[176:177], v[182:183], off
	v_fmac_f32_e32 v169, v180, v180
	v_fmac_f32_e32 v170, v178, v178
	v_add_f32_e32 v169, v169, v170
	v_add_f32_e32 v168, v168, v169
	s_nop 0
	v_lshlrev_b32_e32 v176, 16, v186
	v_and_b32_e32 v177, 0xffff0000, v186
	v_lshlrev_b32_e32 v182, 16, v187
	v_and_b32_e32 v183, 0xffff0000, v187
	v_pk_add_f32 v[182:183], v[16:17], v[182:183]
	v_pk_add_f32 v[176:177], v[14:15], v[176:177]
	v_mul_f32_e32 v170, v183, v183
	v_cvt_pk_bf16_f32 v186, v176, v177
	v_cvt_pk_bf16_f32 v187, v182, v183
	v_mov_b64_e32 v[188:189], v[230:231]
	v_mul_f32_e32 v169, v177, v177
	v_fmac_f32_e32 v169, v176, v176
	v_fmac_f32_e32 v170, v182, v182
	v_add_f32_e32 v169, v169, v170
	v_add_f32_e32 v178, v168, v169
	global_store_dwordx2 v[184:185], v[186:187], off
	s_nop 0
	v_lshlrev_b32_e32 v168, 16, v188
	v_and_b32_e32 v169, 0xffff0000, v188
	v_lshlrev_b32_e32 v170, 16, v189
	v_and_b32_e32 v171, 0xffff0000, v189
	v_pk_add_f32 v[170:171], v[12:13], v[170:171]
	v_pk_add_f32 v[168:169], v[10:11], v[168:169]
	s_nop 0
	v_cvt_pk_bf16_f32 v176, v168, v169
	v_cvt_pk_bf16_f32 v177, v170, v171
	v_mul_f32_e32 v169, v169, v169
	v_mul_f32_e32 v171, v171, v171
	v_fmac_f32_e32 v169, v168, v168
	v_fmac_f32_e32 v171, v170, v170
	global_store_dwordx2 v[166:167], v[176:177], off
	v_add_f32_e32 v166, v169, v171
	v_add_f32_e32 v166, v178, v166
	v_mov_b32_e32 v167, v166
	s_nop 1
	v_permlane16_swap_b32_e32 v166, v167
	v_add_f32_e32 v166, v166, v167
	v_mov_b32_e32 v167, v166
	s_nop 1
	v_permlane32_swap_b32_e32 v166, v167
	s_and_saveexec_b64 s[60:61], s[4:5]
	s_cbranch_execz .LBB0_2551
	s_lshl_b32 s0, s10, 2
	s_or_b32 s0, s0, s76
	s_ashr_i32 s1, s0, 31
	s_lshl_b64 s[0:1], s[0:1], 15
	s_add_u32 s0, s72, s0
	s_addc_u32 s1, s73, s1
	v_add_f32_e32 v168, v166, v167
	v_lshl_add_u64 v[166:167], v[160:161], 2, s[0:1]
	global_store_dword v[166:167], v168, off offset:128
.LBB0_2551:
	s_or_b64 exec, exec, s[60:61]
	v_lshl_add_u64 v[166:167], s[58:59], 0, v[142:143]
	v_lshlrev_b64 v[166:167], 11, v[166:167]
	v_lshl_add_u64 v[164:165], v[166:167], 0, v[164:165]
	v_lshlrev_b64 v[164:165], 1, v[164:165]
	v_lshl_add_u64 v[166:167], s[18:19], 0, v[164:165]
	v_mov_b64_e32 v[166:167], v[190:191]
	v_or_b32_e32 v170, 32, v164
	v_mov_b32_e32 v171, v165
	v_lshl_add_u64 v[176:177], s[18:19], 0, v[170:171]
	v_lshl_add_u64 v[180:181], s[20:21], 0, v[164:165]
	v_or_b32_e32 v182, 0x100, v164
	v_mov_b32_e32 v183, v165
	v_lshl_add_u64 v[184:185], s[18:19], 0, v[182:183]
	v_or_b32_e32 v164, 0x120, v164
	v_lshl_add_u64 v[170:171], s[20:21], 0, v[170:171]
	v_lshl_add_u64 v[186:187], s[18:19], 0, v[164:165]
	v_lshl_add_u64 v[182:183], s[20:21], 0, v[182:183]
	v_lshl_add_u64 v[164:165], s[20:21], 0, v[164:165]
	s_nop 0
	v_lshlrev_b32_e32 v168, 16, v166
	v_and_b32_e32 v169, 0xffff0000, v166
	v_lshlrev_b32_e32 v166, 16, v167
	v_and_b32_e32 v167, 0xffff0000, v167
	v_pk_add_f32 v[166:167], v[36:37], v[166:167]
	v_pk_add_f32 v[168:169], v[34:35], v[168:169]
	s_nop 0
	v_cvt_pk_bf16_f32 v178, v168, v169
	v_cvt_pk_bf16_f32 v179, v166, v167
	v_mov_b64_e32 v[176:177], v[192:193]
	v_mul_f32_e32 v169, v169, v169
	global_store_dwordx2 v[180:181], v[178:179], off
	v_mul_f32_e32 v167, v167, v167
	v_fmac_f32_e32 v169, v168, v168
	v_fmac_f32_e32 v167, v166, v166
	v_add_f32_e32 v166, v169, v167
	s_nop 0
	v_lshlrev_b32_e32 v178, 16, v176
	v_and_b32_e32 v179, 0xffff0000, v176
	v_lshlrev_b32_e32 v176, 16, v177
	v_and_b32_e32 v177, 0xffff0000, v177
	v_pk_add_f32 v[176:177], v[28:29], v[176:177]
	v_pk_add_f32 v[178:179], v[26:27], v[178:179]
	v_mul_f32_e32 v168, v177, v177
	v_cvt_pk_bf16_f32 v180, v178, v179
	v_cvt_pk_bf16_f32 v181, v176, v177
	v_mov_b64_e32 v[184:185], v[194:195]
	v_mul_f32_e32 v167, v179, v179
	global_store_dwordx2 v[170:171], v[180:181], off
	v_fmac_f32_e32 v167, v178, v178
	v_fmac_f32_e32 v168, v176, v176
	v_add_f32_e32 v167, v167, v168
	v_add_f32_e32 v166, v166, v167
	s_nop 0
	v_lshlrev_b32_e32 v170, 16, v184
	v_and_b32_e32 v171, 0xffff0000, v184
	v_lshlrev_b32_e32 v180, 16, v185
	v_and_b32_e32 v181, 0xffff0000, v185
	v_pk_add_f32 v[180:181], v[8:9], v[180:181]
	v_pk_add_f32 v[170:171], v[6:7], v[170:171]
	v_mul_f32_e32 v168, v181, v181
	v_cvt_pk_bf16_f32 v184, v170, v171
	v_cvt_pk_bf16_f32 v185, v180, v181
	v_mov_b64_e32 v[186:187], v[196:197]
	v_mul_f32_e32 v167, v171, v171
	v_fmac_f32_e32 v167, v170, v170
	v_fmac_f32_e32 v168, v180, v180
	v_add_f32_e32 v167, v167, v168
	v_add_f32_e32 v176, v166, v167
	global_store_dwordx2 v[182:183], v[184:185], off
	s_nop 0
	v_lshlrev_b32_e32 v166, 16, v186
	v_and_b32_e32 v167, 0xffff0000, v186
	v_lshlrev_b32_e32 v168, 16, v187
	v_and_b32_e32 v169, 0xffff0000, v187
	v_pk_add_f32 v[168:169], v[4:5], v[168:169]
	v_pk_add_f32 v[166:167], v[2:3], v[166:167]
	s_nop 0
	v_cvt_pk_bf16_f32 v170, v166, v167
	v_cvt_pk_bf16_f32 v171, v168, v169
	v_mul_f32_e32 v167, v167, v167
	v_mul_f32_e32 v169, v169, v169
	v_fmac_f32_e32 v167, v166, v166
	v_fmac_f32_e32 v169, v168, v168
	global_store_dwordx2 v[164:165], v[170:171], off
	v_add_f32_e32 v164, v167, v169
	v_add_f32_e32 v164, v176, v164
	v_mov_b32_e32 v165, v164
	s_nop 1
	v_permlane16_swap_b32_e32 v164, v165
	v_add_f32_e32 v164, v164, v165
	v_mov_b32_e32 v165, v164
	s_nop 1
	v_permlane32_swap_b32_e32 v164, v165
	s_and_saveexec_b64 s[58:59], s[4:5]
	s_cbranch_execz .LBB0_2553
	s_lshl_b32 s0, s10, 2
	s_or_b32 s0, s0, s76
	s_ashr_i32 s1, s0, 31
	s_lshl_b64 s[0:1], s[0:1], 15
	s_add_u32 s0, s72, s0
	s_addc_u32 s1, s73, s1
	v_add_f32_e32 v166, v164, v165
	v_lshl_add_u64 v[164:165], v[160:161], 2, s[0:1]
	global_store_dword v[164:165], v166, off offset:192
.LBB0_2553:
	s_or_b64 exec, exec, s[58:59]
	s_mov_b64 s[0:1], 0x80000
	v_lshl_add_u64 v[164:165], v[162:163], 0, s[0:1]
	v_lshl_add_u64 v[166:167], s[18:19], 0, v[164:165]
	v_add_u32_e32 v199, 0x80000, v198
	global_load_dwordx2 v[208:209], v199, s[18:19]
	global_load_dwordx2 v[210:211], v199, s[18:19] offset:32
	global_load_dwordx2 v[212:213], v199, s[18:19] offset:256
	global_load_dwordx2 v[214:215], v199, s[18:19] offset:288
	v_add_u32_e32 v200, 0x90000, v198
	global_load_dwordx2 v[216:217], v200, s[18:19]
	global_load_dwordx2 v[218:219], v200, s[18:19] offset:32
	global_load_dwordx2 v[220:221], v200, s[18:19] offset:256
	global_load_dwordx2 v[222:223], v200, s[18:19] offset:288
	v_add_u32_e32 v201, 0xa0000, v198
	global_load_dwordx2 v[224:225], v201, s[18:19]
	global_load_dwordx2 v[226:227], v201, s[18:19] offset:32
	global_load_dwordx2 v[228:229], v201, s[18:19] offset:256
	global_load_dwordx2 v[230:231], v201, s[18:19] offset:288
	v_add_u32_e32 v202, 0xb0000, v198
	global_load_dwordx2 v[190:191], v202, s[18:19]
	global_load_dwordx2 v[192:193], v202, s[18:19] offset:32
	global_load_dwordx2 v[194:195], v202, s[18:19] offset:256
	global_load_dwordx2 v[196:197], v202, s[18:19] offset:288
	s_waitcnt vmcnt(0)
	v_mov_b64_e32 v[166:167], v[208:209]
	s_mov_b64 s[0:1], 0x80020
	v_lshl_add_u64 v[168:169], v[162:163], 0, s[0:1]
	v_lshl_add_u64 v[170:171], s[18:19], 0, v[168:169]
	s_mov_b64 s[0:1], 0x80100
	v_lshl_add_u64 v[164:165], s[20:21], 0, v[164:165]
	v_lshl_add_u64 v[168:169], s[20:21], 0, v[168:169]
	s_nop 0
	v_lshlrev_b32_e32 v176, 16, v166
	v_and_b32_e32 v177, 0xffff0000, v166
	v_lshlrev_b32_e32 v166, 16, v167
	v_and_b32_e32 v167, 0xffff0000, v167
	v_pk_add_f32 v[128:129], v[128:129], v[166:167]
	v_pk_add_f32 v[126:127], v[126:127], v[176:177]
	v_lshl_add_u64 v[176:177], v[162:163], 0, s[0:1]
	v_cvt_pk_bf16_f32 v166, v126, v127
	v_cvt_pk_bf16_f32 v167, v128, v129
	v_mov_b64_e32 v[170:171], v[210:211]
	v_lshl_add_u64 v[178:179], s[18:19], 0, v[176:177]
	global_store_dwordx2 v[164:165], v[166:167], off
	s_mov_b64 s[0:1], 0x80120
	v_mul_f32_e32 v127, v127, v127
	v_mul_f32_e32 v129, v129, v129
	v_fmac_f32_e32 v127, v126, v126
	v_fmac_f32_e32 v129, v128, v128
	v_add_f32_e32 v126, v127, v129
	s_nop 0
	v_lshlrev_b32_e32 v164, 16, v170
	v_and_b32_e32 v165, 0xffff0000, v170
	v_lshlrev_b32_e32 v166, 16, v171
	v_and_b32_e32 v167, 0xffff0000, v171
	v_pk_add_f32 v[124:125], v[124:125], v[166:167]
	v_pk_add_f32 v[122:123], v[122:123], v[164:165]
	v_lshl_add_u64 v[170:171], v[162:163], 0, s[0:1]
	v_cvt_pk_bf16_f32 v164, v122, v123
	v_cvt_pk_bf16_f32 v165, v124, v125
	v_mov_b64_e32 v[166:167], v[212:213]
	v_lshl_add_u64 v[178:179], s[18:19], 0, v[170:171]
	global_store_dwordx2 v[168:169], v[164:165], off
	v_mul_f32_e32 v123, v123, v123
	v_mul_f32_e32 v125, v125, v125
	v_fmac_f32_e32 v123, v122, v122
	v_fmac_f32_e32 v125, v124, v124
	v_add_f32_e32 v122, v123, v125
	v_add_f32_e32 v122, v126, v122
	v_lshl_add_u64 v[168:169], s[20:21], 0, v[176:177]
	v_lshl_add_u64 v[170:171], s[20:21], 0, v[170:171]
	s_nop 0
	v_lshlrev_b32_e32 v164, 16, v166
	v_and_b32_e32 v165, 0xffff0000, v166
	v_lshlrev_b32_e32 v166, 16, v167
	v_and_b32_e32 v167, 0xffff0000, v167
	v_pk_add_f32 v[120:121], v[120:121], v[166:167]
	v_pk_add_f32 v[118:119], v[118:119], v[164:165]
	s_nop 0
	v_cvt_pk_bf16_f32 v164, v118, v119
	v_cvt_pk_bf16_f32 v165, v120, v121
	v_mov_b64_e32 v[166:167], v[214:215]
	v_mul_f32_e32 v119, v119, v119
	v_mul_f32_e32 v121, v121, v121
	v_fmac_f32_e32 v119, v118, v118
	v_fmac_f32_e32 v121, v120, v120
	v_add_f32_e32 v118, v119, v121
	v_add_f32_e32 v122, v122, v118
	global_store_dwordx2 v[168:169], v[164:165], off
	s_nop 0
	v_lshlrev_b32_e32 v118, 16, v166
	v_and_b32_e32 v119, 0xffff0000, v166
	v_lshlrev_b32_e32 v120, 16, v167
	v_and_b32_e32 v121, 0xffff0000, v167
	v_pk_add_f32 v[116:117], v[116:117], v[120:121]
	v_pk_add_f32 v[114:115], v[114:115], v[118:119]
	s_nop 0
	v_cvt_pk_bf16_f32 v118, v114, v115
	v_cvt_pk_bf16_f32 v119, v116, v117
	v_mul_f32_e32 v115, v115, v115
	v_mul_f32_e32 v117, v117, v117
	v_fmac_f32_e32 v115, v114, v114
	v_fmac_f32_e32 v117, v116, v116
	v_add_f32_e32 v114, v115, v117
	v_add_f32_e32 v114, v122, v114
	v_mov_b32_e32 v115, v114
	s_nop 1
	v_permlane16_swap_b32_e32 v114, v115
	v_add_f32_e32 v114, v114, v115
	v_mov_b32_e32 v115, v114
	s_nop 1
	v_permlane32_swap_b32_e32 v114, v115
	global_store_dwordx2 v[170:171], v[118:119], off
	s_and_saveexec_b64 s[58:59], s[4:5]
	s_cbranch_execz .LBB0_2555
	s_lshl_b32 s0, s10, 2
	s_or_b32 s0, s0, s76
	s_ashr_i32 s1, s0, 31
	s_lshl_b64 s[0:1], s[0:1], 15
	s_add_u32 s0, s72, s0
	s_addc_u32 s1, s73, s1
	v_add_f32_e32 v116, v114, v115
	v_lshl_add_u64 v[114:115], v[160:161], 2, s[0:1]
	global_store_dword v[114:115], v116, off offset:512
.LBB0_2555:
	s_or_b64 exec, exec, s[58:59]
	s_mov_b64 s[0:1], 0x90000
	v_lshl_add_u64 v[114:115], v[162:163], 0, s[0:1]
	v_lshl_add_u64 v[116:117], s[18:19], 0, v[114:115]
	v_mov_b64_e32 v[116:117], v[216:217]
	s_mov_b64 s[0:1], 0x90020
	v_lshl_add_u64 v[118:119], v[162:163], 0, s[0:1]
	v_lshl_add_u64 v[120:121], s[18:19], 0, v[118:119]
	s_mov_b64 s[0:1], 0x90100
	v_lshl_add_u64 v[114:115], s[20:21], 0, v[114:115]
	v_lshl_add_u64 v[118:119], s[20:21], 0, v[118:119]
	s_nop 0
	v_lshlrev_b32_e32 v122, 16, v116
	v_and_b32_e32 v123, 0xffff0000, v116
	v_lshlrev_b32_e32 v116, 16, v117
	v_and_b32_e32 v117, 0xffff0000, v117
	v_pk_add_f32 v[112:113], v[112:113], v[116:117]
	v_pk_add_f32 v[110:111], v[110:111], v[122:123]
	v_lshl_add_u64 v[122:123], v[162:163], 0, s[0:1]
	v_cvt_pk_bf16_f32 v116, v110, v111
	v_cvt_pk_bf16_f32 v117, v112, v113
	v_mov_b64_e32 v[120:121], v[218:219]
	v_lshl_add_u64 v[124:125], s[18:19], 0, v[122:123]
	global_store_dwordx2 v[114:115], v[116:117], off
	s_mov_b64 s[0:1], 0x90120
	v_mul_f32_e32 v111, v111, v111
	v_mul_f32_e32 v113, v113, v113
	v_fmac_f32_e32 v111, v110, v110
	v_fmac_f32_e32 v113, v112, v112
	v_add_f32_e32 v110, v111, v113
	s_nop 0
	v_lshlrev_b32_e32 v114, 16, v120
	v_and_b32_e32 v115, 0xffff0000, v120
	v_lshlrev_b32_e32 v116, 16, v121
	v_and_b32_e32 v117, 0xffff0000, v121
	v_pk_add_f32 v[108:109], v[108:109], v[116:117]
	v_pk_add_f32 v[106:107], v[106:107], v[114:115]
	v_lshl_add_u64 v[120:121], v[162:163], 0, s[0:1]
	v_cvt_pk_bf16_f32 v114, v106, v107
	v_cvt_pk_bf16_f32 v115, v108, v109
	v_mov_b64_e32 v[116:117], v[220:221]
	v_lshl_add_u64 v[124:125], s[18:19], 0, v[120:121]
	global_store_dwordx2 v[118:119], v[114:115], off
	v_mul_f32_e32 v107, v107, v107
	v_mul_f32_e32 v109, v109, v109
	v_fmac_f32_e32 v107, v106, v106
	v_fmac_f32_e32 v109, v108, v108
	v_add_f32_e32 v106, v107, v109
	v_add_f32_e32 v106, v110, v106
	v_lshl_add_u64 v[118:119], s[20:21], 0, v[122:123]
	v_lshl_add_u64 v[120:121], s[20:21], 0, v[120:121]
	s_nop 0
	v_lshlrev_b32_e32 v114, 16, v116
	v_and_b32_e32 v115, 0xffff0000, v116
	v_lshlrev_b32_e32 v116, 16, v117
	v_and_b32_e32 v117, 0xffff0000, v117
	v_pk_add_f32 v[104:105], v[104:105], v[116:117]
	v_pk_add_f32 v[102:103], v[102:103], v[114:115]
	s_nop 0
	v_cvt_pk_bf16_f32 v114, v102, v103
	v_cvt_pk_bf16_f32 v115, v104, v105
	v_mov_b64_e32 v[116:117], v[222:223]
	v_mul_f32_e32 v103, v103, v103
	v_mul_f32_e32 v105, v105, v105
	v_fmac_f32_e32 v103, v102, v102
	v_fmac_f32_e32 v105, v104, v104
	v_add_f32_e32 v102, v103, v105
	v_add_f32_e32 v106, v106, v102
	global_store_dwordx2 v[118:119], v[114:115], off
	s_nop 0
	v_lshlrev_b32_e32 v102, 16, v116
	v_and_b32_e32 v103, 0xffff0000, v116
	v_lshlrev_b32_e32 v104, 16, v117
	v_and_b32_e32 v105, 0xffff0000, v117
	v_pk_add_f32 v[100:101], v[100:101], v[104:105]
	v_pk_add_f32 v[98:99], v[98:99], v[102:103]
	s_nop 0
	v_cvt_pk_bf16_f32 v102, v98, v99
	v_cvt_pk_bf16_f32 v103, v100, v101
	v_mul_f32_e32 v99, v99, v99
	v_mul_f32_e32 v101, v101, v101
	v_fmac_f32_e32 v99, v98, v98
	v_fmac_f32_e32 v101, v100, v100
	v_add_f32_e32 v98, v99, v101
	v_add_f32_e32 v98, v106, v98
	v_mov_b32_e32 v99, v98
	s_nop 1
	v_permlane16_swap_b32_e32 v98, v99
	v_add_f32_e32 v98, v98, v99
	v_mov_b32_e32 v99, v98
	s_nop 1
	v_permlane32_swap_b32_e32 v98, v99
	global_store_dwordx2 v[120:121], v[102:103], off
	s_and_saveexec_b64 s[58:59], s[4:5]
	s_cbranch_execz .LBB0_2557
	s_lshl_b32 s0, s10, 2
	s_or_b32 s0, s0, s76
	s_ashr_i32 s1, s0, 31
	s_lshl_b64 s[0:1], s[0:1], 15
	s_add_u32 s0, s72, s0
	s_addc_u32 s1, s73, s1
	v_add_f32_e32 v100, v98, v99
	v_lshl_add_u64 v[98:99], v[160:161], 2, s[0:1]
	global_store_dword v[98:99], v100, off offset:576
.LBB0_2557:
	s_or_b64 exec, exec, s[58:59]
	v_lshl_add_u64 v[98:99], v[162:163], 0, s[26:27]
	v_lshl_add_u64 v[100:101], s[18:19], 0, v[98:99]
	v_mov_b64_e32 v[100:101], v[224:225]
	v_lshl_add_u64 v[102:103], v[162:163], 0, s[28:29]
	v_lshl_add_u64 v[104:105], s[18:19], 0, v[102:103]
	v_lshl_add_u64 v[98:99], s[20:21], 0, v[98:99]
	v_lshl_add_u64 v[102:103], s[20:21], 0, v[102:103]
	s_nop 0
	v_lshlrev_b32_e32 v106, 16, v100
	v_and_b32_e32 v107, 0xffff0000, v100
	v_lshlrev_b32_e32 v100, 16, v101
	v_and_b32_e32 v101, 0xffff0000, v101
	v_pk_add_f32 v[96:97], v[96:97], v[100:101]
	v_pk_add_f32 v[94:95], v[94:95], v[106:107]
	v_lshl_add_u64 v[106:107], v[162:163], 0, s[30:31]
	v_cvt_pk_bf16_f32 v100, v94, v95
	v_cvt_pk_bf16_f32 v101, v96, v97
	v_mov_b64_e32 v[104:105], v[226:227]
	v_lshl_add_u64 v[108:109], s[18:19], 0, v[106:107]
	global_store_dwordx2 v[98:99], v[100:101], off
	v_mul_f32_e32 v95, v95, v95
	v_mul_f32_e32 v97, v97, v97
	v_fmac_f32_e32 v95, v94, v94
	v_fmac_f32_e32 v97, v96, v96
	v_add_f32_e32 v94, v95, v97
	s_nop 0
	v_lshlrev_b32_e32 v98, 16, v104
	v_and_b32_e32 v99, 0xffff0000, v104
	v_lshlrev_b32_e32 v100, 16, v105
	v_and_b32_e32 v101, 0xffff0000, v105
	v_pk_add_f32 v[92:93], v[92:93], v[100:101]
	v_pk_add_f32 v[90:91], v[90:91], v[98:99]
	v_lshl_add_u64 v[104:105], v[162:163], 0, s[34:35]
	v_cvt_pk_bf16_f32 v98, v90, v91
	v_cvt_pk_bf16_f32 v99, v92, v93
	v_mov_b64_e32 v[100:101], v[228:229]
	v_lshl_add_u64 v[108:109], s[18:19], 0, v[104:105]
	global_store_dwordx2 v[102:103], v[98:99], off
	v_mul_f32_e32 v91, v91, v91
	v_mul_f32_e32 v93, v93, v93
	v_fmac_f32_e32 v91, v90, v90
	v_fmac_f32_e32 v93, v92, v92
	v_add_f32_e32 v90, v91, v93
	v_add_f32_e32 v90, v94, v90
	v_lshl_add_u64 v[102:103], s[20:21], 0, v[106:107]
	v_lshl_add_u64 v[104:105], s[20:21], 0, v[104:105]
	s_nop 0
	v_lshlrev_b32_e32 v98, 16, v100
	v_and_b32_e32 v99, 0xffff0000, v100
	v_lshlrev_b32_e32 v100, 16, v101
	v_and_b32_e32 v101, 0xffff0000, v101
	v_pk_add_f32 v[88:89], v[88:89], v[100:101]
	v_pk_add_f32 v[86:87], v[86:87], v[98:99]
	s_nop 0
	v_cvt_pk_bf16_f32 v98, v86, v87
	v_cvt_pk_bf16_f32 v99, v88, v89
	v_mov_b64_e32 v[100:101], v[230:231]
	v_mul_f32_e32 v87, v87, v87
	v_mul_f32_e32 v89, v89, v89
	v_fmac_f32_e32 v87, v86, v86
	v_fmac_f32_e32 v89, v88, v88
	v_add_f32_e32 v86, v87, v89
	v_add_f32_e32 v90, v90, v86
	global_store_dwordx2 v[102:103], v[98:99], off
	s_nop 0
	v_lshlrev_b32_e32 v86, 16, v100
	v_and_b32_e32 v87, 0xffff0000, v100
	v_lshlrev_b32_e32 v88, 16, v101
	v_and_b32_e32 v89, 0xffff0000, v101
	v_pk_add_f32 v[84:85], v[84:85], v[88:89]
	v_pk_add_f32 v[82:83], v[82:83], v[86:87]
	s_nop 0
	v_cvt_pk_bf16_f32 v86, v82, v83
	v_cvt_pk_bf16_f32 v87, v84, v85
	v_mul_f32_e32 v83, v83, v83
	v_mul_f32_e32 v85, v85, v85
	v_fmac_f32_e32 v83, v82, v82
	v_fmac_f32_e32 v85, v84, v84
	v_add_f32_e32 v82, v83, v85
	v_add_f32_e32 v82, v90, v82
	v_mov_b32_e32 v83, v82
	s_nop 1
	v_permlane16_swap_b32_e32 v82, v83
	v_add_f32_e32 v82, v82, v83
	v_mov_b32_e32 v83, v82
	s_nop 1
	v_permlane32_swap_b32_e32 v82, v83
	global_store_dwordx2 v[104:105], v[86:87], off
	s_and_saveexec_b64 s[58:59], s[4:5]
	s_cbranch_execz .LBB0_2559
	s_lshl_b32 s0, s10, 2
	s_or_b32 s0, s0, s76
	s_ashr_i32 s1, s0, 31
	s_lshl_b64 s[0:1], s[0:1], 15
	s_add_u32 s0, s72, s0
	s_addc_u32 s1, s73, s1
	v_add_f32_e32 v84, v82, v83
	v_lshl_add_u64 v[82:83], v[160:161], 2, s[0:1]
	global_store_dword v[82:83], v84, off offset:640
.LBB0_2559:
	s_or_b64 exec, exec, s[58:59]
	v_lshl_add_u64 v[82:83], v[162:163], 0, s[36:37]
	v_lshl_add_u64 v[84:85], s[18:19], 0, v[82:83]
	v_mov_b64_e32 v[84:85], v[190:191]
	v_lshl_add_u64 v[86:87], v[162:163], 0, s[40:41]
	v_lshl_add_u64 v[88:89], s[18:19], 0, v[86:87]
	v_lshl_add_u64 v[82:83], s[20:21], 0, v[82:83]
	v_lshl_add_u64 v[86:87], s[20:21], 0, v[86:87]
	s_nop 0
	v_lshlrev_b32_e32 v90, 16, v84
	v_and_b32_e32 v91, 0xffff0000, v84
	v_lshlrev_b32_e32 v84, 16, v85
	v_and_b32_e32 v85, 0xffff0000, v85
	v_pk_add_f32 v[80:81], v[80:81], v[84:85]
	v_pk_add_f32 v[78:79], v[78:79], v[90:91]
	v_lshl_add_u64 v[90:91], v[162:163], 0, s[42:43]
	v_cvt_pk_bf16_f32 v84, v78, v79
	v_cvt_pk_bf16_f32 v85, v80, v81
	v_mov_b64_e32 v[88:89], v[192:193]
	v_lshl_add_u64 v[92:93], s[18:19], 0, v[90:91]
	global_store_dwordx2 v[82:83], v[84:85], off
	v_mul_f32_e32 v79, v79, v79
	v_mul_f32_e32 v81, v81, v81
	v_fmac_f32_e32 v79, v78, v78
	v_fmac_f32_e32 v81, v80, v80
	v_add_f32_e32 v78, v79, v81
	s_nop 0
	v_lshlrev_b32_e32 v82, 16, v88
	v_and_b32_e32 v83, 0xffff0000, v88
	v_lshlrev_b32_e32 v84, 16, v89
	v_and_b32_e32 v85, 0xffff0000, v89
	v_pk_add_f32 v[76:77], v[76:77], v[84:85]
	v_pk_add_f32 v[74:75], v[74:75], v[82:83]
	v_lshl_add_u64 v[88:89], v[162:163], 0, s[44:45]
	v_cvt_pk_bf16_f32 v82, v74, v75
	v_cvt_pk_bf16_f32 v83, v76, v77
	v_mov_b64_e32 v[84:85], v[194:195]
	v_lshl_add_u64 v[92:93], s[18:19], 0, v[88:89]
	global_store_dwordx2 v[86:87], v[82:83], off
	v_mul_f32_e32 v75, v75, v75
	v_mul_f32_e32 v77, v77, v77
	v_fmac_f32_e32 v75, v74, v74
	v_fmac_f32_e32 v77, v76, v76
	v_add_f32_e32 v74, v75, v77
	v_add_f32_e32 v74, v78, v74
	v_lshl_add_u64 v[86:87], s[20:21], 0, v[90:91]
	v_lshl_add_u64 v[88:89], s[20:21], 0, v[88:89]
	s_nop 0
	v_lshlrev_b32_e32 v82, 16, v84
	v_and_b32_e32 v83, 0xffff0000, v84
	v_lshlrev_b32_e32 v84, 16, v85
	v_and_b32_e32 v85, 0xffff0000, v85
	v_pk_add_f32 v[72:73], v[72:73], v[84:85]
	v_pk_add_f32 v[70:71], v[70:71], v[82:83]
	s_nop 0
	v_cvt_pk_bf16_f32 v82, v70, v71
	v_cvt_pk_bf16_f32 v83, v72, v73
	v_mov_b64_e32 v[84:85], v[196:197]
	v_mul_f32_e32 v71, v71, v71
	v_mul_f32_e32 v73, v73, v73
	v_fmac_f32_e32 v71, v70, v70
	v_fmac_f32_e32 v73, v72, v72
	v_add_f32_e32 v70, v71, v73
	v_add_f32_e32 v74, v74, v70
	global_store_dwordx2 v[86:87], v[82:83], off
	s_nop 0
	v_lshlrev_b32_e32 v70, 16, v84
	v_and_b32_e32 v71, 0xffff0000, v84
	v_lshlrev_b32_e32 v72, 16, v85
	v_and_b32_e32 v73, 0xffff0000, v85
	v_pk_add_f32 v[20:21], v[20:21], v[72:73]
	v_pk_add_f32 v[18:19], v[18:19], v[70:71]
	s_nop 0
	v_cvt_pk_bf16_f32 v70, v18, v19
	v_cvt_pk_bf16_f32 v71, v20, v21
	v_mul_f32_e32 v19, v19, v19
	v_mul_f32_e32 v21, v21, v21
	v_fmac_f32_e32 v19, v18, v18
	v_fmac_f32_e32 v21, v20, v20
	v_add_f32_e32 v18, v19, v21
	v_add_f32_e32 v18, v74, v18
	v_mov_b32_e32 v19, v18
	s_nop 1
	v_permlane16_swap_b32_e32 v18, v19
	v_add_f32_e32 v18, v18, v19
	v_mov_b32_e32 v19, v18
	s_nop 1
	v_permlane32_swap_b32_e32 v18, v19
	global_store_dwordx2 v[88:89], v[70:71], off
	s_and_saveexec_b64 s[58:59], s[4:5]
	s_cbranch_execz .LBB0_2561
	s_lshl_b32 s0, s10, 2
	s_or_b32 s0, s0, s76
	s_ashr_i32 s1, s0, 31
	s_lshl_b64 s[0:1], s[0:1], 15
	s_add_u32 s0, s72, s0
	s_addc_u32 s1, s73, s1
	v_add_f32_e32 v20, v18, v19
	v_lshl_add_u64 v[18:19], v[160:161], 2, s[0:1]
	global_store_dword v[18:19], v20, off offset:704
